# K loops: DMA address adds of segments 2 and 4 hoisted into the wave's own preceding MFMA segment, plus the extra priority windows
# baseline (speedup 1.0000x reference)
; #define PG8_STAGE(bufoff, gbase, voff) do { _Pragma("unroll") for (int _i = 0; _i < 2; ++_i) \
;         __builtin_amdgcn_global_load_lds((const unsigned*)((const char*)(gbase) + (voff)[_i]), (LAS unsigned*)(lds + (bufoff) + ldsw + _i * 8192), 16, 0, 0); } while (0)
; #define PG8_LDA(dst, b, h) do { _Pragma("unroll") for (int m = 0; m < 4; ++m) _Pragma("unroll") for (int k = 0; k < 2; ++k) dst[m][k] = *(const LAS bf16x8*)(lds + PG8_SA(b, h) + aoff + m * 2048 + k * 1024); } while (0)
; #define PG8_LDB(dst, b, h) do { _Pragma("unroll") for (int n = 0; n < 2; ++n) _Pragma("unroll") for (int k = 0; k < 2; ++k) dst[n][k] = *(const LAS bf16x8*)(lds + PG8_SB(b, h) + boff + n * 2048 + k * 1024); } while (0)
; #define PG8_MMA(ai, bj, At, Bt) do { __builtin_amdgcn_s_setprio(1); _Pragma("unroll") for (int m = 0; m < 4; ++m) _Pragma("unroll") for (int n = 0; n < 2; ++n) _Pragma("unroll") for (int k = 0; k < 2; ++k) \
;         acc[ai][bj][m][n] = __builtin_amdgcn_mfma_f32_16x16x32_bf16(Bt[n][k], At[m][k], acc[ai][bj][m][n], 0, 0, 0); __builtin_amdgcn_s_setprio(0); } while (0)
; #define PG8_WAIT_V(n) asm volatile("s_waitcnt vmcnt(" #n ")" ::: "memory")
; #define PG8_WAIT_L(n) asm volatile("s_waitcnt lgkmcnt(" #n ")" ::: "memory")
; #define PG8_BAR __builtin_amdgcn_s_barrier()
; #define PG8_SCHED __builtin_amdgcn_sched_barrier(0)
; template <bool PERM>
; __device__ __forceinline__ void gemm_phase(LAS unsigned char* lds, const Gemm g, const Sched& S, const EpiDesc& E, const Ctx& C) {
;     ...
;         for (int t = 0; t < nt; t += 2) {
;             const bool last = (t == nt - 2);
;             const char* a1 = cA + (size_t)(t + 1) * kstep;
;             const char* a2 = last ? nA : cA + (size_t)(t + 2) * kstep; const char* b2 = last ? nB : cB + (size_t)(t + 2) * kstep;
;             const char* a3 = a2 + kstep; const char* b3 = b2 + kstep;
;             PG8_LDB(B0, 0, 0); PG8_LDB(B1, 0, 1); PG8_SCHED; PG8_LDA(At, 0, 0); PG8_STAGE(PG8_SA(1, 1), a1 + hstepA, voffA);
;             PG8_WAIT_V(8); PG8_WAIT_L(0); PG8_BAR; PG8_MMA(0, 0, At, B0); PG8_MMA(0, 1, At, B1); PG8_BAR; PG8_SCHED;
;             PG8_LDA(At, 0, 1); PG8_STAGE(PG8_SB(0, 0), b2, voffB); PG8_STAGE(PG8_SB(0, 1), b2 + hstepB, voffB); PG8_STAGE(PG8_SA(0, 0), a2, voffA);
;             PG8_WAIT_V(8); PG8_WAIT_L(0); PG8_BAR; PG8_MMA(1, 0, At, B0); PG8_MMA(1, 1, At, B1); PG8_BAR; PG8_SCHED;
.Lka_wd:
.Lka_peel:
	s_add_i32 s37, s20, 2
	s_add_u32 s40, s2, 0x80
	s_addc_u32 s21, s3, 0
	s_add_i32 s61, 0, 0x10000
	s_cmp_eq_u32 s22, s20
	s_cselect_b32 s21, s63, s21
	s_cselect_b32 s20, s62, s40
	v_add_u32_e32 v0, s61, v248
	s_cselect_b32 s41, s65, s36
	s_cselect_b32 s40, s64, s23
	s_add_i32 s88, 0, 0x14000
	ds_read_b128 v[130:133], v0
	ds_read_b128 v[134:137], v0 offset:1024
	ds_read_b128 v[138:141], v0 offset:2048
	ds_read_b128 v[142:145], v0 offset:3072
	v_add_u32_e32 v0, s88, v248
	ds_read_b128 v[146:149], v0
	ds_read_b128 v[150:153], v0 offset:1024
	ds_read_b128 v[154:157], v0 offset:2048
	ds_read_b128 v[158:161], v0 offset:3072
	v_lshl_add_u64 v[192:193], s[2:3], 0, v[180:181]
	s_add_i32 m0, s69, 0xc000
	ds_read_b128 v[162:165], v250
	ds_read_b128 v[184:187], v250 offset:1024
	ds_read_b128 v[188:191], v250 offset:2048
	ds_read_b128 v[196:199], v250 offset:3072
	ds_read_b128 v[200:203], v250 offset:4096
	ds_read_b128 v[204:207], v250 offset:5120
	ds_read_b128 v[208:211], v250 offset:6144
	ds_read_b128 v[212:215], v250 offset:7168
	global_load_lds_dwordx4 v[192:193], off
	v_lshl_add_u64 v[192:193], s[2:3], 0, v[182:183]
	s_add_i32 m0, s69, 0xe000
	s_nop 0
	global_load_lds_dwordx4 v[192:193], off
	s_nop 0
	s_waitcnt lgkmcnt(0)
	s_barrier
	s_setprio 1
	s_waitcnt lgkmcnt(0)
	v_mfma_f32_16x16x32_bf16 v[126:129], v[130:133], v[162:165], 0
	v_mfma_f32_16x16x32_bf16 v[122:125], v[138:141], v[162:165], 0
	v_lshl_add_u64 v[192:193], s[40:41], 0, v[170:171]
	v_mfma_f32_16x16x32_bf16 v[110:113], v[130:133], v[188:191], 0
	v_mfma_f32_16x16x32_bf16 v[106:109], v[138:141], v[188:191], 0
	v_lshl_add_u64 v[216:217], s[40:41], 0, v[174:175]
	v_mfma_f32_16x16x32_bf16 v[94:97], v[130:133], v[200:203], 0
	v_mfma_f32_16x16x32_bf16 v[90:93], v[138:141], v[200:203], 0
	s_add_u32 s40, s40, s42
	s_addc_u32 s41, s41, 0
	v_mfma_f32_16x16x32_bf16 v[78:81], v[130:133], v[208:211], 0
	v_mfma_f32_16x16x32_bf16 v[74:77], v[138:141], v[208:211], 0
	v_lshl_add_u64 v[218:219], s[40:41], 0, v[170:171]
	s_setprio 0
	s_setprio 1
	v_mfma_f32_16x16x32_bf16 v[126:129], v[134:137], v[184:187], v[126:129]
	v_mfma_f32_16x16x32_bf16 v[122:125], v[142:145], v[184:187], v[122:125]
	v_lshl_add_u64 v[220:221], s[40:41], 0, v[174:175]
	v_mfma_f32_16x16x32_bf16 v[110:113], v[134:137], v[196:199], v[110:113]
	v_mfma_f32_16x16x32_bf16 v[106:109], v[142:145], v[196:199], v[106:109]
	v_lshl_add_u64 v[222:223], s[20:21], 0, v[168:169]
	v_mfma_f32_16x16x32_bf16 v[94:97], v[134:137], v[204:207], v[94:97]
	v_mfma_f32_16x16x32_bf16 v[90:93], v[142:145], v[204:207], v[90:93]
	v_lshl_add_u64 v[224:225], s[20:21], 0, v[172:173]
	v_mfma_f32_16x16x32_bf16 v[78:81], v[134:137], v[212:215], v[78:81]
	v_mfma_f32_16x16x32_bf16 v[74:77], v[142:145], v[212:215], v[74:77]
	s_setprio 0
	s_setprio 1
	v_mfma_f32_16x16x32_bf16 v[118:121], v[146:149], v[162:165], 0
	v_mfma_f32_16x16x32_bf16 v[114:117], v[154:157], v[162:165], 0
	v_mfma_f32_16x16x32_bf16 v[102:105], v[146:149], v[188:191], 0
	v_mfma_f32_16x16x32_bf16 v[98:101], v[154:157], v[188:191], 0
	v_mfma_f32_16x16x32_bf16 v[86:89], v[146:149], v[200:203], 0
	v_mfma_f32_16x16x32_bf16 v[82:85], v[154:157], v[200:203], 0
	v_mfma_f32_16x16x32_bf16 v[70:73], v[146:149], v[208:211], 0
	v_mfma_f32_16x16x32_bf16 v[66:69], v[154:157], v[208:211], 0
	s_setprio 0
	s_setprio 1
	v_mfma_f32_16x16x32_bf16 v[118:121], v[150:153], v[184:187], v[118:121]
	v_mfma_f32_16x16x32_bf16 v[114:117], v[158:161], v[184:187], v[114:117]
	v_mfma_f32_16x16x32_bf16 v[102:105], v[150:153], v[196:199], v[102:105]
	v_mfma_f32_16x16x32_bf16 v[98:101], v[158:161], v[196:199], v[98:101]
	v_mfma_f32_16x16x32_bf16 v[86:89], v[150:153], v[204:207], v[86:89]
	v_mfma_f32_16x16x32_bf16 v[82:85], v[158:161], v[204:207], v[82:85]
	v_mfma_f32_16x16x32_bf16 v[70:73], v[150:153], v[212:215], v[70:73]
	v_mfma_f32_16x16x32_bf16 v[66:69], v[158:161], v[212:215], v[66:69]
	s_setprio 0
	s_barrier
	s_add_i32 s61, s61, s68
	s_mov_b32 m0, s61
	ds_read_b128 v[162:165], v250 offset:16384
	ds_read_b128 v[184:187], v250 offset:17408
	ds_read_b128 v[188:191], v250 offset:18432
	ds_read_b128 v[196:199], v250 offset:19456
	ds_read_b128 v[200:203], v250 offset:20480
	ds_read_b128 v[204:207], v250 offset:21504
	ds_read_b128 v[208:211], v250 offset:22528
	ds_read_b128 v[212:215], v250 offset:23552
	global_load_lds_dwordx4 v[192:193], off
	s_add_i32 m0, s61, 0x2000
	s_add_i32 s61, s88, s68
	global_load_lds_dwordx4 v[216:217], off
	s_mov_b32 m0, s61
	s_nop 0
	global_load_lds_dwordx4 v[218:219], off
	s_add_i32 m0, s61, 0x2000
	s_nop 0
	global_load_lds_dwordx4 v[220:221], off
	s_mov_b32 m0, s69
	s_nop 0
	global_load_lds_dwordx4 v[222:223], off
	s_mov_b32 m0, s70
	s_nop 0
	global_load_lds_dwordx4 v[224:225], off
	s_nop 0
	s_waitcnt lgkmcnt(0)
	s_barrier
; #define PG8_STAGE(bufoff, gbase, voff) do { _Pragma("unroll") for (int _i = 0; _i < 2; ++_i) \
;         __builtin_amdgcn_global_load_lds((const unsigned*)((const char*)(gbase) + (voff)[_i]), (LAS unsigned*)(lds + (bufoff) + ldsw + _i * 8192), 16, 0, 0); } while (0)
; #define PG8_LDA(dst, b, h) do { _Pragma("unroll") for (int m = 0; m < 4; ++m) _Pragma("unroll") for (int k = 0; k < 2; ++k) dst[m][k] = *(const LAS bf16x8*)(lds + PG8_SA(b, h) + aoff + m * 2048 + k * 1024); } while (0)
; #define PG8_LDB(dst, b, h) do { _Pragma("unroll") for (int n = 0; n < 2; ++n) _Pragma("unroll") for (int k = 0; k < 2; ++k) dst[n][k] = *(const LAS bf16x8*)(lds + PG8_SB(b, h) + boff + n * 2048 + k * 1024); } while (0)
; #define PG8_MMA(ai, bj, At, Bt) do { __builtin_amdgcn_s_setprio(1); _Pragma("unroll") for (int m = 0; m < 4; ++m) _Pragma("unroll") for (int n = 0; n < 2; ++n) _Pragma("unroll") for (int k = 0; k < 2; ++k) \
;         acc[ai][bj][m][n] = __builtin_amdgcn_mfma_f32_16x16x32_bf16(Bt[n][k], At[m][k], acc[ai][bj][m][n], 0, 0, 0); __builtin_amdgcn_s_setprio(0); } while (0)
; #define PG8_WAIT_V(n) asm volatile("s_waitcnt vmcnt(" #n ")" ::: "memory")
; #define PG8_WAIT_L(n) asm volatile("s_waitcnt lgkmcnt(" #n ")" ::: "memory")
; #define PG8_BAR __builtin_amdgcn_s_barrier()
; #define PG8_SCHED __builtin_amdgcn_sched_barrier(0)
; template <bool PERM>
; __device__ __forceinline__ void gemm_phase(LAS unsigned char* lds, const Gemm g, const Sched& S, const EpiDesc& E, const Ctx& C) {
;     ...
;             PG8_LDA(At, 0, 1); PG8_STAGE(PG8_SB(0, 0), b2, voffB); PG8_STAGE(PG8_SB(0, 1), b2 + hstepB, voffB); PG8_STAGE(PG8_SA(0, 0), a2, voffA);
;             PG8_WAIT_V(8); PG8_WAIT_L(0); PG8_BAR; PG8_MMA(1, 0, At, B0); PG8_MMA(1, 1, At, B1); PG8_BAR; PG8_SCHED;
;             PG8_LDB(B0, 1, 0); PG8_LDB(B1, 1, 1); PG8_SCHED; PG8_LDA(At, 1, 0); PG8_STAGE(PG8_SA(0, 1), a2 + hstepA, voffA);
;             PG8_WAIT_V(8); PG8_WAIT_L(0); PG8_BAR; PG8_MMA(0, 0, At, B0); PG8_MMA(0, 1, At, B1); PG8_BAR; PG8_SCHED;
	s_setprio 1
	s_waitcnt lgkmcnt(0)
	v_mfma_f32_16x16x32_bf16 v[62:65], v[130:133], v[162:165], 0
	v_mfma_f32_16x16x32_bf16 v[58:61], v[138:141], v[162:165], 0
	v_mfma_f32_16x16x32_bf16 v[46:49], v[130:133], v[188:191], 0
	v_mfma_f32_16x16x32_bf16 v[42:45], v[138:141], v[188:191], 0
	v_mfma_f32_16x16x32_bf16 v[30:33], v[130:133], v[200:203], 0
	v_mfma_f32_16x16x32_bf16 v[26:29], v[138:141], v[200:203], 0
	v_mfma_f32_16x16x32_bf16 v[14:17], v[130:133], v[208:211], 0
	v_mfma_f32_16x16x32_bf16 v[10:13], v[138:141], v[208:211], 0
	s_setprio 0
	s_setprio 1
	v_mfma_f32_16x16x32_bf16 v[62:65], v[134:137], v[184:187], v[62:65]
	v_mfma_f32_16x16x32_bf16 v[58:61], v[142:145], v[184:187], v[58:61]
	v_mfma_f32_16x16x32_bf16 v[46:49], v[134:137], v[196:199], v[46:49]
	v_mfma_f32_16x16x32_bf16 v[42:45], v[142:145], v[196:199], v[42:45]
	v_mfma_f32_16x16x32_bf16 v[30:33], v[134:137], v[204:207], v[30:33]
	v_mfma_f32_16x16x32_bf16 v[26:29], v[142:145], v[204:207], v[26:29]
	v_mfma_f32_16x16x32_bf16 v[14:17], v[134:137], v[212:215], v[14:17]
	v_mfma_f32_16x16x32_bf16 v[10:13], v[142:145], v[212:215], v[10:13]
	s_setprio 0
	s_setprio 1
	v_mfma_f32_16x16x32_bf16 v[54:57], v[146:149], v[162:165], 0
	v_mfma_f32_16x16x32_bf16 v[50:53], v[154:157], v[162:165], 0
	v_mfma_f32_16x16x32_bf16 v[38:41], v[146:149], v[188:191], 0
	v_mfma_f32_16x16x32_bf16 v[34:37], v[154:157], v[188:191], 0
	v_mfma_f32_16x16x32_bf16 v[22:25], v[146:149], v[200:203], 0
	v_mfma_f32_16x16x32_bf16 v[18:21], v[154:157], v[200:203], 0
	v_mfma_f32_16x16x32_bf16 v[6:9], v[146:149], v[208:211], 0
	v_mfma_f32_16x16x32_bf16 v[2:5], v[154:157], v[208:211], 0
	s_setprio 0
	s_setprio 1
	v_mfma_f32_16x16x32_bf16 v[54:57], v[150:153], v[184:187], v[54:57]
	v_mfma_f32_16x16x32_bf16 v[50:53], v[158:161], v[184:187], v[50:53]
	v_mfma_f32_16x16x32_bf16 v[38:41], v[150:153], v[196:199], v[38:41]
	v_mfma_f32_16x16x32_bf16 v[34:37], v[158:161], v[196:199], v[34:37]
	v_mfma_f32_16x16x32_bf16 v[22:25], v[150:153], v[204:207], v[22:25]
	v_mfma_f32_16x16x32_bf16 v[18:21], v[158:161], v[204:207], v[18:21]
	v_mfma_f32_16x16x32_bf16 v[6:9], v[150:153], v[212:215], v[6:9]
	v_mfma_f32_16x16x32_bf16 v[2:5], v[158:161], v[212:215], v[2:5]
	s_setprio 0
	s_barrier
	s_add_i32 s40, 0, 0x18000
	v_add_u32_e32 v0, s40, v248
	s_add_i32 s41, 0, 0x1c000
	ds_read_b128 v[130:133], v0
	ds_read_b128 v[134:137], v0 offset:1024
	ds_read_b128 v[138:141], v0 offset:2048
	ds_read_b128 v[142:145], v0 offset:3072
	v_add_u32_e32 v0, s41, v248
	ds_read_b128 v[146:149], v0
	ds_read_b128 v[150:153], v0 offset:1024
	ds_read_b128 v[154:157], v0 offset:2048
	ds_read_b128 v[158:161], v0 offset:3072
	s_add_u32 s20, s20, s42
	s_addc_u32 s21, s21, 0
	s_mov_b32 m0, s71
	v_lshl_add_u64 v[226:227], s[20:21], 0, v[168:169]
	ds_read_b128 v[162:165], v250 offset:32768
	ds_read_b128 v[184:187], v250 offset:33792
	ds_read_b128 v[188:191], v250 offset:34816
	ds_read_b128 v[196:199], v250 offset:35840
	ds_read_b128 v[200:203], v250 offset:36864
	ds_read_b128 v[204:207], v250 offset:37888
	ds_read_b128 v[208:211], v250 offset:38912
	ds_read_b128 v[212:215], v250 offset:39936
	global_load_lds_dwordx4 v[226:227], off
	v_lshl_add_u64 v[226:227], s[20:21], 0, v[172:173]
	s_mov_b32 m0, s72
	s_nop 0
	global_load_lds_dwordx4 v[226:227], off
	s_waitcnt vmcnt(8)
	s_waitcnt lgkmcnt(0)
	s_barrier
	s_setprio 1
	s_waitcnt lgkmcnt(0)
	v_mfma_f32_16x16x32_bf16 v[126:129], v[130:133], v[162:165], v[126:129]
	v_mfma_f32_16x16x32_bf16 v[122:125], v[138:141], v[162:165], v[122:125]
	v_lshl_add_u64 v[192:193], v[192:193], 0, s[46:47]
	v_mfma_f32_16x16x32_bf16 v[110:113], v[130:133], v[188:191], v[110:113]
	v_mfma_f32_16x16x32_bf16 v[106:109], v[138:141], v[188:191], v[106:109]
	v_lshl_add_u64 v[216:217], v[216:217], 0, s[46:47]
	v_mfma_f32_16x16x32_bf16 v[94:97], v[130:133], v[200:203], v[94:97]
	v_mfma_f32_16x16x32_bf16 v[90:93], v[138:141], v[200:203], v[90:93]
	v_lshl_add_u64 v[218:219], v[218:219], 0, s[46:47]
	v_mfma_f32_16x16x32_bf16 v[78:81], v[130:133], v[208:211], v[78:81]
	v_mfma_f32_16x16x32_bf16 v[74:77], v[138:141], v[208:211], v[74:77]
	v_lshl_add_u64 v[220:221], v[220:221], 0, s[46:47]
	s_setprio 0
	s_setprio 1
	v_mfma_f32_16x16x32_bf16 v[126:129], v[134:137], v[184:187], v[126:129]
	v_mfma_f32_16x16x32_bf16 v[122:125], v[142:145], v[184:187], v[122:125]
	v_lshl_add_u64 v[222:223], v[222:223], 0, s[46:47]
	v_mfma_f32_16x16x32_bf16 v[110:113], v[134:137], v[196:199], v[110:113]
	v_mfma_f32_16x16x32_bf16 v[106:109], v[142:145], v[196:199], v[106:109]
	v_lshl_add_u64 v[224:225], v[224:225], 0, s[46:47]
	v_mfma_f32_16x16x32_bf16 v[94:97], v[134:137], v[204:207], v[94:97]
	v_mfma_f32_16x16x32_bf16 v[90:93], v[142:145], v[204:207], v[90:93]
	v_mfma_f32_16x16x32_bf16 v[78:81], v[134:137], v[212:215], v[78:81]
	v_mfma_f32_16x16x32_bf16 v[74:77], v[142:145], v[212:215], v[74:77]
	s_setprio 0
	s_setprio 1
	v_mfma_f32_16x16x32_bf16 v[118:121], v[146:149], v[162:165], v[118:121]
	v_mfma_f32_16x16x32_bf16 v[114:117], v[154:157], v[162:165], v[114:117]
	v_mfma_f32_16x16x32_bf16 v[102:105], v[146:149], v[188:191], v[102:105]
	v_mfma_f32_16x16x32_bf16 v[98:101], v[154:157], v[188:191], v[98:101]
	v_mfma_f32_16x16x32_bf16 v[86:89], v[146:149], v[200:203], v[86:89]
	v_mfma_f32_16x16x32_bf16 v[82:85], v[154:157], v[200:203], v[82:85]
	v_mfma_f32_16x16x32_bf16 v[70:73], v[146:149], v[208:211], v[70:73]
	v_mfma_f32_16x16x32_bf16 v[66:69], v[154:157], v[208:211], v[66:69]
	s_setprio 0
	s_setprio 1
	v_mfma_f32_16x16x32_bf16 v[118:121], v[150:153], v[184:187], v[118:121]
	v_mfma_f32_16x16x32_bf16 v[114:117], v[158:161], v[184:187], v[114:117]
	v_mfma_f32_16x16x32_bf16 v[102:105], v[150:153], v[196:199], v[102:105]
	v_mfma_f32_16x16x32_bf16 v[98:101], v[158:161], v[196:199], v[98:101]
	v_mfma_f32_16x16x32_bf16 v[86:89], v[150:153], v[204:207], v[86:89]
	v_mfma_f32_16x16x32_bf16 v[82:85], v[158:161], v[204:207], v[82:85]
	v_mfma_f32_16x16x32_bf16 v[70:73], v[150:153], v[212:215], v[70:73]
	v_mfma_f32_16x16x32_bf16 v[66:69], v[158:161], v[212:215], v[66:69]
	s_setprio 0
	s_barrier
; #define PG8_STAGE(bufoff, gbase, voff) do { _Pragma("unroll") for (int _i = 0; _i < 2; ++_i) \
;         __builtin_amdgcn_global_load_lds((const unsigned*)((const char*)(gbase) + (voff)[_i]), (LAS unsigned*)(lds + (bufoff) + ldsw + _i * 8192), 16, 0, 0); } while (0)
; #define PG8_LDA(dst, b, h) do { _Pragma("unroll") for (int m = 0; m < 4; ++m) _Pragma("unroll") for (int k = 0; k < 2; ++k) dst[m][k] = *(const LAS bf16x8*)(lds + PG8_SA(b, h) + aoff + m * 2048 + k * 1024); } while (0)
; #define PG8_LDB(dst, b, h) do { _Pragma("unroll") for (int n = 0; n < 2; ++n) _Pragma("unroll") for (int k = 0; k < 2; ++k) dst[n][k] = *(const LAS bf16x8*)(lds + PG8_SB(b, h) + boff + n * 2048 + k * 1024); } while (0)
; #define PG8_MMA(ai, bj, At, Bt) do { __builtin_amdgcn_s_setprio(1); _Pragma("unroll") for (int m = 0; m < 4; ++m) _Pragma("unroll") for (int n = 0; n < 2; ++n) _Pragma("unroll") for (int k = 0; k < 2; ++k) \
;         acc[ai][bj][m][n] = __builtin_amdgcn_mfma_f32_16x16x32_bf16(Bt[n][k], At[m][k], acc[ai][bj][m][n], 0, 0, 0); __builtin_amdgcn_s_setprio(0); } while (0)
; #define PG8_WAIT_V(n) asm volatile("s_waitcnt vmcnt(" #n ")" ::: "memory")
; #define PG8_WAIT_L(n) asm volatile("s_waitcnt lgkmcnt(" #n ")" ::: "memory")
; #define PG8_BAR __builtin_amdgcn_s_barrier()
; #define PG8_SCHED __builtin_amdgcn_sched_barrier(0)
; template <bool PERM>
; __device__ __forceinline__ void gemm_phase(LAS unsigned char* lds, const Gemm g, const Sched& S, const EpiDesc& E, const Ctx& C) {
;     ...
;         for (int t = 0; t < nt; t += 2) {
;             const bool last = (t == nt - 2);
;             const char* a1 = cA + (size_t)(t + 1) * kstep;
;             const char* a2 = last ? nA : cA + (size_t)(t + 2) * kstep; const char* b2 = last ? nB : cB + (size_t)(t + 2) * kstep;
;             const char* a3 = a2 + kstep; const char* b3 = b2 + kstep;
;             PG8_LDB(B0, 0, 0); PG8_LDB(B1, 0, 1); PG8_SCHED; PG8_LDA(At, 0, 0); PG8_STAGE(PG8_SA(1, 1), a1 + hstepA, voffA);
;     ...
;             PG8_LDA(At, 1, 1); PG8_STAGE(PG8_SB(1, 0), b3, voffB); PG8_STAGE(PG8_SB(1, 1), b3 + hstepB, voffB); PG8_STAGE(PG8_SA(1, 0), a3, voffA);
;             PG8_WAIT_V(8); PG8_WAIT_L(0); PG8_BAR; PG8_MMA(1, 0, At, B0); PG8_MMA(1, 1, At, B1); PG8_BAR; PG8_SCHED;
	s_add_i32 s20, s40, s68
	s_mov_b32 m0, s20
	ds_read_b128 v[162:165], v250 offset:49152
	ds_read_b128 v[184:187], v250 offset:50176
	ds_read_b128 v[188:191], v250 offset:51200
	ds_read_b128 v[196:199], v250 offset:52224
	ds_read_b128 v[200:203], v250 offset:53248
	ds_read_b128 v[204:207], v250 offset:54272
	ds_read_b128 v[208:211], v250 offset:55296
	ds_read_b128 v[212:215], v250 offset:56320
	global_load_lds_dwordx4 v[192:193], off
	s_add_i32 m0, s20, 0x2000
	s_add_i32 s20, s41, s68
	global_load_lds_dwordx4 v[216:217], off
	s_mov_b32 m0, s20
	s_nop 0
	global_load_lds_dwordx4 v[218:219], off
	s_add_i32 m0, s20, 0x2000
	s_nop 0
	global_load_lds_dwordx4 v[220:221], off
	s_mov_b32 m0, s75
	s_nop 0
	global_load_lds_dwordx4 v[222:223], off
	s_mov_b32 m0, s76
	s_nop 0
	global_load_lds_dwordx4 v[224:225], off
	s_waitcnt vmcnt(8)
	s_waitcnt lgkmcnt(0)
	s_barrier
	s_setprio 1
	s_waitcnt lgkmcnt(0)
	v_mfma_f32_16x16x32_bf16 v[62:65], v[130:133], v[162:165], v[62:65]
	v_mfma_f32_16x16x32_bf16 v[58:61], v[138:141], v[162:165], v[58:61]
	v_mfma_f32_16x16x32_bf16 v[46:49], v[130:133], v[188:191], v[46:49]
	v_mfma_f32_16x16x32_bf16 v[42:45], v[138:141], v[188:191], v[42:45]
	v_mfma_f32_16x16x32_bf16 v[30:33], v[130:133], v[200:203], v[30:33]
	v_mfma_f32_16x16x32_bf16 v[26:29], v[138:141], v[200:203], v[26:29]
	v_mfma_f32_16x16x32_bf16 v[14:17], v[130:133], v[208:211], v[14:17]
	v_mfma_f32_16x16x32_bf16 v[10:13], v[138:141], v[208:211], v[10:13]
	s_setprio 0
	s_setprio 1
	v_mfma_f32_16x16x32_bf16 v[62:65], v[134:137], v[184:187], v[62:65]
	v_mfma_f32_16x16x32_bf16 v[58:61], v[142:145], v[184:187], v[58:61]
	v_mfma_f32_16x16x32_bf16 v[46:49], v[134:137], v[196:199], v[46:49]
	v_mfma_f32_16x16x32_bf16 v[42:45], v[142:145], v[196:199], v[42:45]
	v_mfma_f32_16x16x32_bf16 v[30:33], v[134:137], v[204:207], v[30:33]
	v_mfma_f32_16x16x32_bf16 v[26:29], v[142:145], v[204:207], v[26:29]
	v_mfma_f32_16x16x32_bf16 v[14:17], v[134:137], v[212:215], v[14:17]
	v_mfma_f32_16x16x32_bf16 v[10:13], v[142:145], v[212:215], v[10:13]
	s_setprio 0
	s_setprio 1
	v_mfma_f32_16x16x32_bf16 v[54:57], v[146:149], v[162:165], v[54:57]
	v_mfma_f32_16x16x32_bf16 v[50:53], v[154:157], v[162:165], v[50:53]
	v_mfma_f32_16x16x32_bf16 v[38:41], v[146:149], v[188:191], v[38:41]
	v_mfma_f32_16x16x32_bf16 v[34:37], v[154:157], v[188:191], v[34:37]
	v_mfma_f32_16x16x32_bf16 v[22:25], v[146:149], v[200:203], v[22:25]
	v_mfma_f32_16x16x32_bf16 v[18:21], v[154:157], v[200:203], v[18:21]
	v_mfma_f32_16x16x32_bf16 v[6:9], v[146:149], v[208:211], v[6:9]
	v_mfma_f32_16x16x32_bf16 v[2:5], v[154:157], v[208:211], v[2:5]
	s_setprio 0
	s_setprio 1
	v_mfma_f32_16x16x32_bf16 v[54:57], v[150:153], v[184:187], v[54:57]
	v_mfma_f32_16x16x32_bf16 v[50:53], v[158:161], v[184:187], v[50:53]
	v_mfma_f32_16x16x32_bf16 v[38:41], v[150:153], v[196:199], v[38:41]
	v_mfma_f32_16x16x32_bf16 v[34:37], v[158:161], v[196:199], v[34:37]
	v_mfma_f32_16x16x32_bf16 v[22:25], v[150:153], v[204:207], v[22:25]
	v_mfma_f32_16x16x32_bf16 v[18:21], v[158:161], v[204:207], v[18:21]
	v_mfma_f32_16x16x32_bf16 v[6:9], v[150:153], v[212:215], v[6:9]
	v_mfma_f32_16x16x32_bf16 v[2:5], v[158:161], v[212:215], v[2:5]
	s_setprio 0
	s_barrier
	s_add_u32 s2, s2, 0x100
	s_addc_u32 s3, s3, 0
	s_add_u32 s23, s23, 0x100
	s_addc_u32 s36, s36, 0
	s_cmp_ge_i32 s37, s29
	s_mov_b32 s20, s37
	s_cbranch_scc1 .Lka_exit
.LBB0_62:
	s_add_i32 s37, s20, 2
	s_add_u32 s40, s2, 0x80
	s_addc_u32 s21, s3, 0
	s_add_i32 s61, 0, 0x10000
	s_cmp_eq_u32 s22, s20
	s_cselect_b32 s21, s63, s21
	s_cselect_b32 s20, s62, s40
	v_add_u32_e32 v0, s61, v248
	s_cselect_b32 s41, s65, s36
	s_cselect_b32 s40, s64, s23
	s_add_i32 s88, 0, 0x14000
	ds_read_b128 v[130:133], v0
	ds_read_b128 v[134:137], v0 offset:1024
	ds_read_b128 v[138:141], v0 offset:2048
	ds_read_b128 v[142:145], v0 offset:3072
	v_add_u32_e32 v0, s88, v248
	ds_read_b128 v[146:149], v0
	ds_read_b128 v[150:153], v0 offset:1024
	ds_read_b128 v[154:157], v0 offset:2048
	ds_read_b128 v[158:161], v0 offset:3072
	v_lshl_add_u64 v[192:193], s[2:3], 0, v[180:181]
	s_add_i32 m0, s69, 0xc000
	ds_read_b128 v[162:165], v250
	ds_read_b128 v[184:187], v250 offset:1024
	ds_read_b128 v[188:191], v250 offset:2048
	ds_read_b128 v[196:199], v250 offset:3072
	ds_read_b128 v[200:203], v250 offset:4096
	ds_read_b128 v[204:207], v250 offset:5120
	ds_read_b128 v[208:211], v250 offset:6144
	ds_read_b128 v[212:215], v250 offset:7168
	global_load_lds_dwordx4 v[192:193], off
	v_lshl_add_u64 v[192:193], s[2:3], 0, v[182:183]
	s_add_i32 m0, s69, 0xe000
	s_nop 0
	global_load_lds_dwordx4 v[192:193], off
	s_waitcnt vmcnt(8)
	s_waitcnt lgkmcnt(0)
	s_barrier
; #define PG8_STAGE(bufoff, gbase, voff) do { _Pragma("unroll") for (int _i = 0; _i < 2; ++_i) \
;         __builtin_amdgcn_global_load_lds((const unsigned*)((const char*)(gbase) + (voff)[_i]), (LAS unsigned*)(lds + (bufoff) + ldsw + _i * 8192), 16, 0, 0); } while (0)
; #define PG8_LDA(dst, b, h) do { _Pragma("unroll") for (int m = 0; m < 4; ++m) _Pragma("unroll") for (int k = 0; k < 2; ++k) dst[m][k] = *(const LAS bf16x8*)(lds + PG8_SA(b, h) + aoff + m * 2048 + k * 1024); } while (0)
; #define PG8_LDB(dst, b, h) do { _Pragma("unroll") for (int n = 0; n < 2; ++n) _Pragma("unroll") for (int k = 0; k < 2; ++k) dst[n][k] = *(const LAS bf16x8*)(lds + PG8_SB(b, h) + boff + n * 2048 + k * 1024); } while (0)
; #define PG8_MMA(ai, bj, At, Bt) do { __builtin_amdgcn_s_setprio(1); _Pragma("unroll") for (int m = 0; m < 4; ++m) _Pragma("unroll") for (int n = 0; n < 2; ++n) _Pragma("unroll") for (int k = 0; k < 2; ++k) \
;         acc[ai][bj][m][n] = __builtin_amdgcn_mfma_f32_16x16x32_bf16(Bt[n][k], At[m][k], acc[ai][bj][m][n], 0, 0, 0); __builtin_amdgcn_s_setprio(0); } while (0)
; #define PG8_WAIT_V(n) asm volatile("s_waitcnt vmcnt(" #n ")" ::: "memory")
; #define PG8_WAIT_L(n) asm volatile("s_waitcnt lgkmcnt(" #n ")" ::: "memory")
; #define PG8_BAR __builtin_amdgcn_s_barrier()
; #define PG8_SCHED __builtin_amdgcn_sched_barrier(0)
; template <bool PERM>
; __device__ __forceinline__ void gemm_phase(LAS unsigned char* lds, const Gemm g, const Sched& S, const EpiDesc& E, const Ctx& C) {
;     ...
;             PG8_LDB(B0, 0, 0); PG8_LDB(B1, 0, 1); PG8_SCHED; PG8_LDA(At, 0, 0); PG8_STAGE(PG8_SA(1, 1), a1 + hstepA, voffA);
;             PG8_WAIT_V(8); PG8_WAIT_L(0); PG8_BAR; PG8_MMA(0, 0, At, B0); PG8_MMA(0, 1, At, B1); PG8_BAR; PG8_SCHED;
;             PG8_LDA(At, 0, 1); PG8_STAGE(PG8_SB(0, 0), b2, voffB); PG8_STAGE(PG8_SB(0, 1), b2 + hstepB, voffB); PG8_STAGE(PG8_SA(0, 0), a2, voffA);
;             PG8_WAIT_V(8); PG8_WAIT_L(0); PG8_BAR; PG8_MMA(1, 0, At, B0); PG8_MMA(1, 1, At, B1); PG8_BAR; PG8_SCHED;
	s_setprio 1
	s_waitcnt lgkmcnt(0)
	v_mfma_f32_16x16x32_bf16 v[126:129], v[130:133], v[162:165], v[126:129]
	v_mfma_f32_16x16x32_bf16 v[122:125], v[138:141], v[162:165], v[122:125]
	v_lshl_add_u64 v[192:193], s[40:41], 0, v[170:171]
	v_mfma_f32_16x16x32_bf16 v[110:113], v[130:133], v[188:191], v[110:113]
	v_mfma_f32_16x16x32_bf16 v[106:109], v[138:141], v[188:191], v[106:109]
	v_lshl_add_u64 v[216:217], s[40:41], 0, v[174:175]
	v_mfma_f32_16x16x32_bf16 v[94:97], v[130:133], v[200:203], v[94:97]
	v_mfma_f32_16x16x32_bf16 v[90:93], v[138:141], v[200:203], v[90:93]
	s_add_u32 s40, s40, s42
	s_addc_u32 s41, s41, 0
	v_mfma_f32_16x16x32_bf16 v[78:81], v[130:133], v[208:211], v[78:81]
	v_mfma_f32_16x16x32_bf16 v[74:77], v[138:141], v[208:211], v[74:77]
	v_lshl_add_u64 v[218:219], s[40:41], 0, v[170:171]
	s_setprio 0
	s_setprio 1
	v_mfma_f32_16x16x32_bf16 v[126:129], v[134:137], v[184:187], v[126:129]
	v_mfma_f32_16x16x32_bf16 v[122:125], v[142:145], v[184:187], v[122:125]
	v_lshl_add_u64 v[220:221], s[40:41], 0, v[174:175]
	v_mfma_f32_16x16x32_bf16 v[110:113], v[134:137], v[196:199], v[110:113]
	v_mfma_f32_16x16x32_bf16 v[106:109], v[142:145], v[196:199], v[106:109]
	v_lshl_add_u64 v[222:223], s[20:21], 0, v[168:169]
	v_mfma_f32_16x16x32_bf16 v[94:97], v[134:137], v[204:207], v[94:97]
	v_mfma_f32_16x16x32_bf16 v[90:93], v[142:145], v[204:207], v[90:93]
	v_lshl_add_u64 v[224:225], s[20:21], 0, v[172:173]
	v_mfma_f32_16x16x32_bf16 v[78:81], v[134:137], v[212:215], v[78:81]
	v_mfma_f32_16x16x32_bf16 v[74:77], v[142:145], v[212:215], v[74:77]
	s_setprio 0
	s_setprio 1
	v_mfma_f32_16x16x32_bf16 v[118:121], v[146:149], v[162:165], v[118:121]
	v_mfma_f32_16x16x32_bf16 v[114:117], v[154:157], v[162:165], v[114:117]
	v_mfma_f32_16x16x32_bf16 v[102:105], v[146:149], v[188:191], v[102:105]
	v_mfma_f32_16x16x32_bf16 v[98:101], v[154:157], v[188:191], v[98:101]
	v_mfma_f32_16x16x32_bf16 v[86:89], v[146:149], v[200:203], v[86:89]
	v_mfma_f32_16x16x32_bf16 v[82:85], v[154:157], v[200:203], v[82:85]
	v_mfma_f32_16x16x32_bf16 v[70:73], v[146:149], v[208:211], v[70:73]
	v_mfma_f32_16x16x32_bf16 v[66:69], v[154:157], v[208:211], v[66:69]
	s_setprio 0
	s_setprio 1
	v_mfma_f32_16x16x32_bf16 v[118:121], v[150:153], v[184:187], v[118:121]
	v_mfma_f32_16x16x32_bf16 v[114:117], v[158:161], v[184:187], v[114:117]
	v_mfma_f32_16x16x32_bf16 v[102:105], v[150:153], v[196:199], v[102:105]
	v_mfma_f32_16x16x32_bf16 v[98:101], v[158:161], v[196:199], v[98:101]
	v_mfma_f32_16x16x32_bf16 v[86:89], v[150:153], v[204:207], v[86:89]
	v_mfma_f32_16x16x32_bf16 v[82:85], v[158:161], v[204:207], v[82:85]
	v_mfma_f32_16x16x32_bf16 v[70:73], v[150:153], v[212:215], v[70:73]
	v_mfma_f32_16x16x32_bf16 v[66:69], v[158:161], v[212:215], v[66:69]
	s_setprio 0
	s_barrier
	s_add_i32 s61, s61, s68
	s_mov_b32 m0, s61
	ds_read_b128 v[162:165], v250 offset:16384
	ds_read_b128 v[184:187], v250 offset:17408
	ds_read_b128 v[188:191], v250 offset:18432
	ds_read_b128 v[196:199], v250 offset:19456
	ds_read_b128 v[200:203], v250 offset:20480
	ds_read_b128 v[204:207], v250 offset:21504
	ds_read_b128 v[208:211], v250 offset:22528
	ds_read_b128 v[212:215], v250 offset:23552
	global_load_lds_dwordx4 v[192:193], off
	s_add_i32 m0, s61, 0x2000
	s_add_i32 s61, s88, s68
	global_load_lds_dwordx4 v[216:217], off
	s_mov_b32 m0, s61
	s_nop 0
	global_load_lds_dwordx4 v[218:219], off
	s_add_i32 m0, s61, 0x2000
	s_nop 0
	global_load_lds_dwordx4 v[220:221], off
	s_mov_b32 m0, s69
	s_nop 0
	global_load_lds_dwordx4 v[222:223], off
	s_mov_b32 m0, s70
	s_nop 0
	global_load_lds_dwordx4 v[224:225], off
	s_waitcnt vmcnt(8)
	s_waitcnt lgkmcnt(0)
	s_barrier
	s_setprio 1
	s_waitcnt lgkmcnt(0)
	v_mfma_f32_16x16x32_bf16 v[62:65], v[130:133], v[162:165], v[62:65]
	v_mfma_f32_16x16x32_bf16 v[58:61], v[138:141], v[162:165], v[58:61]
	v_mfma_f32_16x16x32_bf16 v[46:49], v[130:133], v[188:191], v[46:49]
	v_mfma_f32_16x16x32_bf16 v[42:45], v[138:141], v[188:191], v[42:45]
	v_mfma_f32_16x16x32_bf16 v[30:33], v[130:133], v[200:203], v[30:33]
	v_mfma_f32_16x16x32_bf16 v[26:29], v[138:141], v[200:203], v[26:29]
	v_mfma_f32_16x16x32_bf16 v[14:17], v[130:133], v[208:211], v[14:17]
	v_mfma_f32_16x16x32_bf16 v[10:13], v[138:141], v[208:211], v[10:13]
	s_setprio 0
	s_setprio 1
	v_mfma_f32_16x16x32_bf16 v[62:65], v[134:137], v[184:187], v[62:65]
	v_mfma_f32_16x16x32_bf16 v[58:61], v[142:145], v[184:187], v[58:61]
	v_mfma_f32_16x16x32_bf16 v[46:49], v[134:137], v[196:199], v[46:49]
	v_mfma_f32_16x16x32_bf16 v[42:45], v[142:145], v[196:199], v[42:45]
	v_mfma_f32_16x16x32_bf16 v[30:33], v[134:137], v[204:207], v[30:33]
	v_mfma_f32_16x16x32_bf16 v[26:29], v[142:145], v[204:207], v[26:29]
	v_mfma_f32_16x16x32_bf16 v[14:17], v[134:137], v[212:215], v[14:17]
	v_mfma_f32_16x16x32_bf16 v[10:13], v[142:145], v[212:215], v[10:13]
	s_setprio 0
	s_setprio 1
	v_mfma_f32_16x16x32_bf16 v[54:57], v[146:149], v[162:165], v[54:57]
	v_mfma_f32_16x16x32_bf16 v[50:53], v[154:157], v[162:165], v[50:53]
	v_mfma_f32_16x16x32_bf16 v[38:41], v[146:149], v[188:191], v[38:41]
	v_mfma_f32_16x16x32_bf16 v[34:37], v[154:157], v[188:191], v[34:37]
	v_mfma_f32_16x16x32_bf16 v[22:25], v[146:149], v[200:203], v[22:25]
	v_mfma_f32_16x16x32_bf16 v[18:21], v[154:157], v[200:203], v[18:21]
	v_mfma_f32_16x16x32_bf16 v[6:9], v[146:149], v[208:211], v[6:9]
	v_mfma_f32_16x16x32_bf16 v[2:5], v[154:157], v[208:211], v[2:5]
	s_setprio 0
	s_setprio 1
	v_mfma_f32_16x16x32_bf16 v[54:57], v[150:153], v[184:187], v[54:57]
	v_mfma_f32_16x16x32_bf16 v[50:53], v[158:161], v[184:187], v[50:53]
	v_mfma_f32_16x16x32_bf16 v[38:41], v[150:153], v[196:199], v[38:41]
	v_mfma_f32_16x16x32_bf16 v[34:37], v[158:161], v[196:199], v[34:37]
	v_mfma_f32_16x16x32_bf16 v[22:25], v[150:153], v[204:207], v[22:25]
	v_mfma_f32_16x16x32_bf16 v[18:21], v[158:161], v[204:207], v[18:21]
	v_mfma_f32_16x16x32_bf16 v[6:9], v[150:153], v[212:215], v[6:9]
	v_mfma_f32_16x16x32_bf16 v[2:5], v[158:161], v[212:215], v[2:5]
	s_setprio 0
	s_barrier
; #define PG8_STAGE(bufoff, gbase, voff) do { _Pragma("unroll") for (int _i = 0; _i < 2; ++_i) \
;         __builtin_amdgcn_global_load_lds((const unsigned*)((const char*)(gbase) + (voff)[_i]), (LAS unsigned*)(lds + (bufoff) + ldsw + _i * 8192), 16, 0, 0); } while (0)
; #define PG8_LDA(dst, b, h) do { _Pragma("unroll") for (int m = 0; m < 4; ++m) _Pragma("unroll") for (int k = 0; k < 2; ++k) dst[m][k] = *(const LAS bf16x8*)(lds + PG8_SA(b, h) + aoff + m * 2048 + k * 1024); } while (0)
; #define PG8_LDB(dst, b, h) do { _Pragma("unroll") for (int n = 0; n < 2; ++n) _Pragma("unroll") for (int k = 0; k < 2; ++k) dst[n][k] = *(const LAS bf16x8*)(lds + PG8_SB(b, h) + boff + n * 2048 + k * 1024); } while (0)
; #define PG8_MMA(ai, bj, At, Bt) do { __builtin_amdgcn_s_setprio(1); _Pragma("unroll") for (int m = 0; m < 4; ++m) _Pragma("unroll") for (int n = 0; n < 2; ++n) _Pragma("unroll") for (int k = 0; k < 2; ++k) \
;         acc[ai][bj][m][n] = __builtin_amdgcn_mfma_f32_16x16x32_bf16(Bt[n][k], At[m][k], acc[ai][bj][m][n], 0, 0, 0); __builtin_amdgcn_s_setprio(0); } while (0)
; #define PG8_WAIT_V(n) asm volatile("s_waitcnt vmcnt(" #n ")" ::: "memory")
; #define PG8_WAIT_L(n) asm volatile("s_waitcnt lgkmcnt(" #n ")" ::: "memory")
; #define PG8_BAR __builtin_amdgcn_s_barrier()
; #define PG8_SCHED __builtin_amdgcn_sched_barrier(0)
; template <bool PERM>
; __device__ __forceinline__ void gemm_phase(LAS unsigned char* lds, const Gemm g, const Sched& S, const EpiDesc& E, const Ctx& C) {
;     ...
;             PG8_LDB(B0, 1, 0); PG8_LDB(B1, 1, 1); PG8_SCHED; PG8_LDA(At, 1, 0); PG8_STAGE(PG8_SA(0, 1), a2 + hstepA, voffA);
;             PG8_WAIT_V(8); PG8_WAIT_L(0); PG8_BAR; PG8_MMA(0, 0, At, B0); PG8_MMA(0, 1, At, B1); PG8_BAR; PG8_SCHED;
	s_add_i32 s40, 0, 0x18000
	v_add_u32_e32 v0, s40, v248
	s_add_i32 s41, 0, 0x1c000
	ds_read_b128 v[130:133], v0
	ds_read_b128 v[134:137], v0 offset:1024
	ds_read_b128 v[138:141], v0 offset:2048
	ds_read_b128 v[142:145], v0 offset:3072
	v_add_u32_e32 v0, s41, v248
	ds_read_b128 v[146:149], v0
	ds_read_b128 v[150:153], v0 offset:1024
	ds_read_b128 v[154:157], v0 offset:2048
	ds_read_b128 v[158:161], v0 offset:3072
	s_add_u32 s20, s20, s42
	s_addc_u32 s21, s21, 0
	s_mov_b32 m0, s71
	v_lshl_add_u64 v[226:227], s[20:21], 0, v[168:169]
	ds_read_b128 v[162:165], v250 offset:32768
	ds_read_b128 v[184:187], v250 offset:33792
	ds_read_b128 v[188:191], v250 offset:34816
	ds_read_b128 v[196:199], v250 offset:35840
	ds_read_b128 v[200:203], v250 offset:36864
	ds_read_b128 v[204:207], v250 offset:37888
	ds_read_b128 v[208:211], v250 offset:38912
	ds_read_b128 v[212:215], v250 offset:39936
	global_load_lds_dwordx4 v[226:227], off
	v_lshl_add_u64 v[226:227], s[20:21], 0, v[172:173]
	s_mov_b32 m0, s72
	s_nop 0
	global_load_lds_dwordx4 v[226:227], off
	s_waitcnt vmcnt(8)
	s_waitcnt lgkmcnt(0)
	s_barrier
	s_setprio 1
	s_waitcnt lgkmcnt(0)
	v_mfma_f32_16x16x32_bf16 v[126:129], v[130:133], v[162:165], v[126:129]
	v_mfma_f32_16x16x32_bf16 v[122:125], v[138:141], v[162:165], v[122:125]
	v_lshl_add_u64 v[192:193], v[192:193], 0, s[46:47]
	v_mfma_f32_16x16x32_bf16 v[110:113], v[130:133], v[188:191], v[110:113]
	v_mfma_f32_16x16x32_bf16 v[106:109], v[138:141], v[188:191], v[106:109]
	v_lshl_add_u64 v[216:217], v[216:217], 0, s[46:47]
	v_mfma_f32_16x16x32_bf16 v[94:97], v[130:133], v[200:203], v[94:97]
	v_mfma_f32_16x16x32_bf16 v[90:93], v[138:141], v[200:203], v[90:93]
	v_lshl_add_u64 v[218:219], v[218:219], 0, s[46:47]
	v_mfma_f32_16x16x32_bf16 v[78:81], v[130:133], v[208:211], v[78:81]
	v_mfma_f32_16x16x32_bf16 v[74:77], v[138:141], v[208:211], v[74:77]
	v_lshl_add_u64 v[220:221], v[220:221], 0, s[46:47]
	s_setprio 0
	s_setprio 1
	v_mfma_f32_16x16x32_bf16 v[126:129], v[134:137], v[184:187], v[126:129]
	v_mfma_f32_16x16x32_bf16 v[122:125], v[142:145], v[184:187], v[122:125]
	v_lshl_add_u64 v[222:223], v[222:223], 0, s[46:47]
	v_mfma_f32_16x16x32_bf16 v[110:113], v[134:137], v[196:199], v[110:113]
	v_mfma_f32_16x16x32_bf16 v[106:109], v[142:145], v[196:199], v[106:109]
	v_lshl_add_u64 v[224:225], v[224:225], 0, s[46:47]
	v_mfma_f32_16x16x32_bf16 v[94:97], v[134:137], v[204:207], v[94:97]
	v_mfma_f32_16x16x32_bf16 v[90:93], v[142:145], v[204:207], v[90:93]
	v_mfma_f32_16x16x32_bf16 v[78:81], v[134:137], v[212:215], v[78:81]
	v_mfma_f32_16x16x32_bf16 v[74:77], v[142:145], v[212:215], v[74:77]
	s_setprio 0
	s_setprio 1
	v_mfma_f32_16x16x32_bf16 v[118:121], v[146:149], v[162:165], v[118:121]
	v_mfma_f32_16x16x32_bf16 v[114:117], v[154:157], v[162:165], v[114:117]
	v_mfma_f32_16x16x32_bf16 v[102:105], v[146:149], v[188:191], v[102:105]
	v_mfma_f32_16x16x32_bf16 v[98:101], v[154:157], v[188:191], v[98:101]
	v_mfma_f32_16x16x32_bf16 v[86:89], v[146:149], v[200:203], v[86:89]
	v_mfma_f32_16x16x32_bf16 v[82:85], v[154:157], v[200:203], v[82:85]
	v_mfma_f32_16x16x32_bf16 v[70:73], v[146:149], v[208:211], v[70:73]
	v_mfma_f32_16x16x32_bf16 v[66:69], v[154:157], v[208:211], v[66:69]
	s_setprio 0
	s_setprio 1
	v_mfma_f32_16x16x32_bf16 v[118:121], v[150:153], v[184:187], v[118:121]
	v_mfma_f32_16x16x32_bf16 v[114:117], v[158:161], v[184:187], v[114:117]
	v_mfma_f32_16x16x32_bf16 v[102:105], v[150:153], v[196:199], v[102:105]
	v_mfma_f32_16x16x32_bf16 v[98:101], v[158:161], v[196:199], v[98:101]
	v_mfma_f32_16x16x32_bf16 v[86:89], v[150:153], v[204:207], v[86:89]
	v_mfma_f32_16x16x32_bf16 v[82:85], v[158:161], v[204:207], v[82:85]
	v_mfma_f32_16x16x32_bf16 v[70:73], v[150:153], v[212:215], v[70:73]
	v_mfma_f32_16x16x32_bf16 v[66:69], v[158:161], v[212:215], v[66:69]
	s_setprio 0
	s_barrier
; #define PG8_STAGE(bufoff, gbase, voff) do { _Pragma("unroll") for (int _i = 0; _i < 2; ++_i) \
;         __builtin_amdgcn_global_load_lds((const unsigned*)((const char*)(gbase) + (voff)[_i]), (LAS unsigned*)(lds + (bufoff) + ldsw + _i * 8192), 16, 0, 0); } while (0)
; #define PG8_LDA(dst, b, h) do { _Pragma("unroll") for (int m = 0; m < 4; ++m) _Pragma("unroll") for (int k = 0; k < 2; ++k) dst[m][k] = *(const LAS bf16x8*)(lds + PG8_SA(b, h) + aoff + m * 2048 + k * 1024); } while (0)
; #define PG8_MMA(ai, bj, At, Bt) do { __builtin_amdgcn_s_setprio(1); _Pragma("unroll") for (int m = 0; m < 4; ++m) _Pragma("unroll") for (int n = 0; n < 2; ++n) _Pragma("unroll") for (int k = 0; k < 2; ++k) \
;         acc[ai][bj][m][n] = __builtin_amdgcn_mfma_f32_16x16x32_bf16(Bt[n][k], At[m][k], acc[ai][bj][m][n], 0, 0, 0); __builtin_amdgcn_s_setprio(0); } while (0)
; #define PG8_WAIT_V(n) asm volatile("s_waitcnt vmcnt(" #n ")" ::: "memory")
; #define PG8_WAIT_L(n) asm volatile("s_waitcnt lgkmcnt(" #n ")" ::: "memory")
; #define PG8_BAR __builtin_amdgcn_s_barrier()
; #define PG8_SCHED __builtin_amdgcn_sched_barrier(0)
; template <bool PERM>
; __device__ __forceinline__ void gemm_phase(LAS unsigned char* lds, const Gemm g, const Sched& S, const EpiDesc& E, const Ctx& C) {
;     ...
;             PG8_LDA(At, 1, 1); PG8_STAGE(PG8_SB(1, 0), b3, voffB); PG8_STAGE(PG8_SB(1, 1), b3 + hstepB, voffB); PG8_STAGE(PG8_SA(1, 0), a3, voffA);
;             PG8_WAIT_V(8); PG8_WAIT_L(0); PG8_BAR; PG8_MMA(1, 0, At, B0); PG8_MMA(1, 1, At, B1); PG8_BAR; PG8_SCHED;
;         }
	s_add_i32 s20, s40, s68
	s_mov_b32 m0, s20
	ds_read_b128 v[162:165], v250 offset:49152
	ds_read_b128 v[184:187], v250 offset:50176
	ds_read_b128 v[188:191], v250 offset:51200
	ds_read_b128 v[196:199], v250 offset:52224
	ds_read_b128 v[200:203], v250 offset:53248
	ds_read_b128 v[204:207], v250 offset:54272
	ds_read_b128 v[208:211], v250 offset:55296
	ds_read_b128 v[212:215], v250 offset:56320
	global_load_lds_dwordx4 v[192:193], off
	s_add_i32 m0, s20, 0x2000
	s_add_i32 s20, s41, s68
	global_load_lds_dwordx4 v[216:217], off
	s_mov_b32 m0, s20
	s_nop 0
	global_load_lds_dwordx4 v[218:219], off
	s_add_i32 m0, s20, 0x2000
	s_nop 0
	global_load_lds_dwordx4 v[220:221], off
	s_mov_b32 m0, s75
	s_nop 0
	global_load_lds_dwordx4 v[222:223], off
	s_mov_b32 m0, s76
	s_nop 0
	global_load_lds_dwordx4 v[224:225], off
	s_waitcnt vmcnt(8)
	s_waitcnt lgkmcnt(0)
	s_barrier
	s_setprio 1
	s_waitcnt lgkmcnt(0)
	v_mfma_f32_16x16x32_bf16 v[62:65], v[130:133], v[162:165], v[62:65]
	v_mfma_f32_16x16x32_bf16 v[58:61], v[138:141], v[162:165], v[58:61]
	v_mfma_f32_16x16x32_bf16 v[46:49], v[130:133], v[188:191], v[46:49]
	v_mfma_f32_16x16x32_bf16 v[42:45], v[138:141], v[188:191], v[42:45]
	v_mfma_f32_16x16x32_bf16 v[30:33], v[130:133], v[200:203], v[30:33]
	v_mfma_f32_16x16x32_bf16 v[26:29], v[138:141], v[200:203], v[26:29]
	v_mfma_f32_16x16x32_bf16 v[14:17], v[130:133], v[208:211], v[14:17]
	v_mfma_f32_16x16x32_bf16 v[10:13], v[138:141], v[208:211], v[10:13]
	s_setprio 0
	s_setprio 1
	v_mfma_f32_16x16x32_bf16 v[62:65], v[134:137], v[184:187], v[62:65]
	v_mfma_f32_16x16x32_bf16 v[58:61], v[142:145], v[184:187], v[58:61]
	v_mfma_f32_16x16x32_bf16 v[46:49], v[134:137], v[196:199], v[46:49]
	v_mfma_f32_16x16x32_bf16 v[42:45], v[142:145], v[196:199], v[42:45]
	v_mfma_f32_16x16x32_bf16 v[30:33], v[134:137], v[204:207], v[30:33]
	v_mfma_f32_16x16x32_bf16 v[26:29], v[142:145], v[204:207], v[26:29]
	v_mfma_f32_16x16x32_bf16 v[14:17], v[134:137], v[212:215], v[14:17]
	v_mfma_f32_16x16x32_bf16 v[10:13], v[142:145], v[212:215], v[10:13]
	s_setprio 0
	s_setprio 1
	v_mfma_f32_16x16x32_bf16 v[54:57], v[146:149], v[162:165], v[54:57]
	v_mfma_f32_16x16x32_bf16 v[50:53], v[154:157], v[162:165], v[50:53]
	v_mfma_f32_16x16x32_bf16 v[38:41], v[146:149], v[188:191], v[38:41]
	v_mfma_f32_16x16x32_bf16 v[34:37], v[154:157], v[188:191], v[34:37]
	v_mfma_f32_16x16x32_bf16 v[22:25], v[146:149], v[200:203], v[22:25]
	v_mfma_f32_16x16x32_bf16 v[18:21], v[154:157], v[200:203], v[18:21]
	v_mfma_f32_16x16x32_bf16 v[6:9], v[146:149], v[208:211], v[6:9]
	v_mfma_f32_16x16x32_bf16 v[2:5], v[154:157], v[208:211], v[2:5]
	s_setprio 0
	s_setprio 1
	v_mfma_f32_16x16x32_bf16 v[54:57], v[150:153], v[184:187], v[54:57]
	v_mfma_f32_16x16x32_bf16 v[50:53], v[158:161], v[184:187], v[50:53]
	v_mfma_f32_16x16x32_bf16 v[38:41], v[150:153], v[196:199], v[38:41]
	v_mfma_f32_16x16x32_bf16 v[34:37], v[158:161], v[196:199], v[34:37]
	v_mfma_f32_16x16x32_bf16 v[22:25], v[150:153], v[204:207], v[22:25]
	v_mfma_f32_16x16x32_bf16 v[18:21], v[158:161], v[204:207], v[18:21]
	v_mfma_f32_16x16x32_bf16 v[6:9], v[150:153], v[212:215], v[6:9]
	v_mfma_f32_16x16x32_bf16 v[2:5], v[158:161], v[212:215], v[2:5]
	s_setprio 0
	s_barrier
	s_add_u32 s2, s2, 0x100
	s_addc_u32 s3, s3, 0
	s_add_u32 s23, s23, 0x100
	s_addc_u32 s36, s36, 0
	s_cmp_ge_i32 s37, s29
	s_mov_b32 s20, s37
	s_cbranch_scc0 .LBB0_62

; #define PG8_STAGE(bufoff, gbase, voff) do { _Pragma("unroll") for (int _i = 0; _i < 2; ++_i) \
;         __builtin_amdgcn_global_load_lds((const unsigned*)((const char*)(gbase) + (voff)[_i]), (LAS unsigned*)(lds + (bufoff) + ldsw + _i * 8192), 16, 0, 0); } while (0)
; #define PG8_LDA(dst, b, h) do { _Pragma("unroll") for (int m = 0; m < 4; ++m) _Pragma("unroll") for (int k = 0; k < 2; ++k) dst[m][k] = *(const LAS bf16x8*)(lds + PG8_SA(b, h) + aoff + m * 2048 + k * 1024); } while (0)
; #define PG8_LDB(dst, b, h) do { _Pragma("unroll") for (int n = 0; n < 2; ++n) _Pragma("unroll") for (int k = 0; k < 2; ++k) dst[n][k] = *(const LAS bf16x8*)(lds + PG8_SB(b, h) + boff + n * 2048 + k * 1024); } while (0)
; #define PG8_MMA(ai, bj, At, Bt) do { __builtin_amdgcn_s_setprio(1); _Pragma("unroll") for (int m = 0; m < 4; ++m) _Pragma("unroll") for (int n = 0; n < 2; ++n) _Pragma("unroll") for (int k = 0; k < 2; ++k) \
;         acc[ai][bj][m][n] = __builtin_amdgcn_mfma_f32_16x16x32_bf16(Bt[n][k], At[m][k], acc[ai][bj][m][n], 0, 0, 0); __builtin_amdgcn_s_setprio(0); } while (0)
; #define PG8_WAIT_V(n) asm volatile("s_waitcnt vmcnt(" #n ")" ::: "memory")
; #define PG8_WAIT_L(n) asm volatile("s_waitcnt lgkmcnt(" #n ")" ::: "memory")
; #define PG8_BAR __builtin_amdgcn_s_barrier()
; #define PG8_SCHED __builtin_amdgcn_sched_barrier(0)
; template <bool PERM>
; __device__ __forceinline__ void gemm_phase(LAS unsigned char* lds, const Gemm g, const Sched& S, const EpiDesc& E, const Ctx& C) {
;     ...
;         for (int t = 0; t < nt; t += 2) {
;             const bool last = (t == nt - 2);
;             const char* a1 = cA + (size_t)(t + 1) * kstep;
;             const char* a2 = last ? nA : cA + (size_t)(t + 2) * kstep; const char* b2 = last ? nB : cB + (size_t)(t + 2) * kstep;
;             const char* a3 = a2 + kstep; const char* b3 = b2 + kstep;
;             PG8_LDB(B0, 0, 0); PG8_LDB(B1, 0, 1); PG8_SCHED; PG8_LDA(At, 0, 0); PG8_STAGE(PG8_SA(1, 1), a1 + hstepA, voffA);
;             PG8_WAIT_V(8); PG8_WAIT_L(0); PG8_BAR; PG8_MMA(0, 0, At, B0); PG8_MMA(0, 1, At, B1); PG8_BAR; PG8_SCHED;
;             PG8_LDA(At, 0, 1); PG8_STAGE(PG8_SB(0, 0), b2, voffB); PG8_STAGE(PG8_SB(0, 1), b2 + hstepB, voffB); PG8_STAGE(PG8_SA(0, 0), a2, voffA);
;             PG8_WAIT_V(8); PG8_WAIT_L(0); PG8_BAR; PG8_MMA(1, 0, At, B0); PG8_MMA(1, 1, At, B1); PG8_BAR; PG8_SCHED;
.Lkb_wd:
.Lkb_peel:
	s_add_i32 s36, s20, 2
	s_add_u32 s37, s2, 0x80
	s_addc_u32 s21, s3, 0
	s_add_i32 s44, 0, 0x10000
	s_cmp_eq_u32 s22, s20
	s_cselect_b32 s21, s63, s21
	s_cselect_b32 s20, s62, s37
	v_add_u32_e32 v0, s44, v174
	s_cselect_b32 s43, s65, s29
	s_cselect_b32 s42, s64, s23
	s_add_i32 s37, 0, 0x14000
	s_waitcnt lgkmcnt(0)
	ds_read_b128 v[130:133], v0
	ds_read_b128 v[144:147], v0 offset:1024
	ds_read_b128 v[148:151], v0 offset:2048
	ds_read_b128 v[152:155], v0 offset:3072
	v_add_u32_e32 v0, s37, v174
	ds_read_b128 v[156:159], v0
	ds_read_b128 v[160:163], v0 offset:1024
	ds_read_b128 v[168:171], v0 offset:2048
	ds_read_b128 v[178:181], v0 offset:3072
	v_lshl_add_u64 v[164:165], s[2:3], 0, v[140:141]
	s_add_i32 m0, s70, 0xc000
	ds_read_b128 v[182:185], v177
	ds_read_b128 v[186:189], v177 offset:1024
	ds_read_b128 v[190:193], v177 offset:2048
	ds_read_b128 v[196:199], v177 offset:3072
	ds_read_b128 v[200:203], v177 offset:4096
	ds_read_b128 v[204:207], v177 offset:5120
	ds_read_b128 v[208:211], v177 offset:6144
	ds_read_b128 v[212:215], v177 offset:7168
	global_load_lds_dwordx4 v[164:165], off
	v_lshl_add_u64 v[164:165], s[2:3], 0, v[142:143]
	s_add_i32 m0, s70, 0xe000
	s_nop 0
	global_load_lds_dwordx4 v[164:165], off
	s_nop 0
	s_waitcnt lgkmcnt(0)
	s_barrier
	s_setprio 1
	s_waitcnt lgkmcnt(0)
	v_mfma_f32_16x16x32_bf16 v[122:125], v[130:133], v[182:185], 0
	v_mfma_f32_16x16x32_bf16 v[126:129], v[148:151], v[182:185], 0
	v_lshl_add_u64 v[164:165], s[42:43], 0, v[134:135]
	v_mfma_f32_16x16x32_bf16 v[106:109], v[130:133], v[190:193], 0
	v_mfma_f32_16x16x32_bf16 v[110:113], v[148:151], v[190:193], 0
	v_lshl_add_u64 v[216:217], s[42:43], 0, v[136:137]
	v_mfma_f32_16x16x32_bf16 v[90:93], v[130:133], v[200:203], 0
	v_mfma_f32_16x16x32_bf16 v[94:97], v[148:151], v[200:203], 0
	s_add_u32 s42, s42, s18
	s_addc_u32 s43, s43, 0
	v_mfma_f32_16x16x32_bf16 v[74:77], v[130:133], v[208:211], 0
	v_mfma_f32_16x16x32_bf16 v[78:81], v[148:151], v[208:211], 0
	v_lshl_add_u64 v[218:219], s[42:43], 0, v[134:135]
	s_setprio 0
	s_setprio 1
	v_mfma_f32_16x16x32_bf16 v[122:125], v[144:147], v[186:189], v[122:125]
	v_mfma_f32_16x16x32_bf16 v[126:129], v[152:155], v[186:189], v[126:129]
	v_lshl_add_u64 v[220:221], s[42:43], 0, v[136:137]
	v_mfma_f32_16x16x32_bf16 v[106:109], v[144:147], v[196:199], v[106:109]
	v_mfma_f32_16x16x32_bf16 v[110:113], v[152:155], v[196:199], v[110:113]
	v_lshl_add_u64 v[222:223], s[20:21], 0, v[134:135]
	v_mfma_f32_16x16x32_bf16 v[90:93], v[144:147], v[204:207], v[90:93]
	v_mfma_f32_16x16x32_bf16 v[94:97], v[152:155], v[204:207], v[94:97]
	v_lshl_add_u64 v[224:225], s[20:21], 0, v[136:137]
	v_mfma_f32_16x16x32_bf16 v[74:77], v[144:147], v[212:215], v[74:77]
	v_mfma_f32_16x16x32_bf16 v[78:81], v[152:155], v[212:215], v[78:81]
	s_setprio 0
	s_setprio 1
	v_mfma_f32_16x16x32_bf16 v[114:117], v[156:159], v[182:185], 0
	v_mfma_f32_16x16x32_bf16 v[118:121], v[168:171], v[182:185], 0
	v_mfma_f32_16x16x32_bf16 v[98:101], v[156:159], v[190:193], 0
	v_mfma_f32_16x16x32_bf16 v[102:105], v[168:171], v[190:193], 0
	v_mfma_f32_16x16x32_bf16 v[82:85], v[156:159], v[200:203], 0
	v_mfma_f32_16x16x32_bf16 v[86:89], v[168:171], v[200:203], 0
	v_mfma_f32_16x16x32_bf16 v[66:69], v[156:159], v[208:211], 0
	v_mfma_f32_16x16x32_bf16 v[70:73], v[168:171], v[208:211], 0
	s_setprio 0
	s_setprio 1
	v_mfma_f32_16x16x32_bf16 v[114:117], v[160:163], v[186:189], v[114:117]
	v_mfma_f32_16x16x32_bf16 v[118:121], v[178:181], v[186:189], v[118:121]
	v_mfma_f32_16x16x32_bf16 v[98:101], v[160:163], v[196:199], v[98:101]
	v_mfma_f32_16x16x32_bf16 v[102:105], v[178:181], v[196:199], v[102:105]
	v_mfma_f32_16x16x32_bf16 v[82:85], v[160:163], v[204:207], v[82:85]
	v_mfma_f32_16x16x32_bf16 v[86:89], v[178:181], v[204:207], v[86:89]
	v_mfma_f32_16x16x32_bf16 v[66:69], v[160:163], v[212:215], v[66:69]
	v_mfma_f32_16x16x32_bf16 v[70:73], v[178:181], v[212:215], v[70:73]
	s_setprio 0
	s_barrier
	s_add_i32 s44, s44, s69
	s_mov_b32 m0, s44
	ds_read_b128 v[182:185], v177 offset:16384
	ds_read_b128 v[186:189], v177 offset:17408
	ds_read_b128 v[190:193], v177 offset:18432
	ds_read_b128 v[196:199], v177 offset:19456
	ds_read_b128 v[200:203], v177 offset:20480
	ds_read_b128 v[204:207], v177 offset:21504
	ds_read_b128 v[208:211], v177 offset:22528
	ds_read_b128 v[212:215], v177 offset:23552
	global_load_lds_dwordx4 v[164:165], off
	s_add_i32 m0, s44, 0x2000
	s_add_i32 s37, s37, s69
	global_load_lds_dwordx4 v[216:217], off
	s_mov_b32 m0, s37
	s_nop 0
	global_load_lds_dwordx4 v[218:219], off
	s_add_i32 m0, s37, 0x2000
	s_nop 0
	global_load_lds_dwordx4 v[220:221], off
	s_mov_b32 m0, s70
	s_nop 0
	global_load_lds_dwordx4 v[222:223], off
	s_mov_b32 m0, s71
	s_nop 0
	global_load_lds_dwordx4 v[224:225], off
	s_nop 0
	s_waitcnt lgkmcnt(0)
	s_barrier
; #define PG8_STAGE(bufoff, gbase, voff) do { _Pragma("unroll") for (int _i = 0; _i < 2; ++_i) \
;         __builtin_amdgcn_global_load_lds((const unsigned*)((const char*)(gbase) + (voff)[_i]), (LAS unsigned*)(lds + (bufoff) + ldsw + _i * 8192), 16, 0, 0); } while (0)
; #define PG8_LDA(dst, b, h) do { _Pragma("unroll") for (int m = 0; m < 4; ++m) _Pragma("unroll") for (int k = 0; k < 2; ++k) dst[m][k] = *(const LAS bf16x8*)(lds + PG8_SA(b, h) + aoff + m * 2048 + k * 1024); } while (0)
; #define PG8_LDB(dst, b, h) do { _Pragma("unroll") for (int n = 0; n < 2; ++n) _Pragma("unroll") for (int k = 0; k < 2; ++k) dst[n][k] = *(const LAS bf16x8*)(lds + PG8_SB(b, h) + boff + n * 2048 + k * 1024); } while (0)
; #define PG8_MMA(ai, bj, At, Bt) do { __builtin_amdgcn_s_setprio(1); _Pragma("unroll") for (int m = 0; m < 4; ++m) _Pragma("unroll") for (int n = 0; n < 2; ++n) _Pragma("unroll") for (int k = 0; k < 2; ++k) \
;         acc[ai][bj][m][n] = __builtin_amdgcn_mfma_f32_16x16x32_bf16(Bt[n][k], At[m][k], acc[ai][bj][m][n], 0, 0, 0); __builtin_amdgcn_s_setprio(0); } while (0)
; #define PG8_WAIT_V(n) asm volatile("s_waitcnt vmcnt(" #n ")" ::: "memory")
; #define PG8_BAR __builtin_amdgcn_s_barrier()
; template <bool PERM>
; __device__ __forceinline__ void gemm_phase(LAS unsigned char* lds, const Gemm g, const Sched& S, const EpiDesc& E, const Ctx& C) {
;     ...
;             PG8_LDB(B0, 0, 0); PG8_LDB(B1, 0, 1); PG8_SCHED; PG8_LDA(At, 0, 0); PG8_STAGE(PG8_SA(1, 1), a1 + hstepA, voffA);
;             PG8_WAIT_V(8); PG8_WAIT_L(0); PG8_BAR; PG8_MMA(0, 0, At, B0); PG8_MMA(0, 1, At, B1); PG8_BAR; PG8_SCHED;
;             PG8_LDA(At, 0, 1); PG8_STAGE(PG8_SB(0, 0), b2, voffB); PG8_STAGE(PG8_SB(0, 1), b2 + hstepB, voffB); PG8_STAGE(PG8_SA(0, 0), a2, voffA);
;             PG8_WAIT_V(8); PG8_WAIT_L(0); PG8_BAR; PG8_MMA(1, 0, At, B0); PG8_MMA(1, 1, At, B1); PG8_BAR; PG8_SCHED;
;             PG8_LDB(B0, 1, 0); PG8_LDB(B1, 1, 1); PG8_SCHED; PG8_LDA(At, 1, 0); PG8_STAGE(PG8_SA(0, 1), a2 + hstepA, voffA);
;             PG8_WAIT_V(8); PG8_WAIT_L(0); PG8_BAR; PG8_MMA(0, 0, At, B0); PG8_MMA(0, 1, At, B1); PG8_BAR; PG8_SCHED;
;             PG8_LDA(At, 1, 1); PG8_STAGE(PG8_SB(1, 0), b3, voffB); PG8_STAGE(PG8_SB(1, 1), b3 + hstepB, voffB); PG8_STAGE(PG8_SA(1, 0), a3, voffA);
;             PG8_WAIT_V(8); PG8_WAIT_L(0); PG8_BAR; PG8_MMA(1, 0, At, B0); PG8_MMA(1, 1, At, B1); PG8_BAR; PG8_SCHED;
	s_setprio 1
	s_waitcnt lgkmcnt(0)
	v_mfma_f32_16x16x32_bf16 v[58:61], v[130:133], v[182:185], 0
	v_mfma_f32_16x16x32_bf16 v[62:65], v[148:151], v[182:185], 0
	v_mfma_f32_16x16x32_bf16 v[42:45], v[130:133], v[190:193], 0
	v_mfma_f32_16x16x32_bf16 v[46:49], v[148:151], v[190:193], 0
	v_mfma_f32_16x16x32_bf16 v[26:29], v[130:133], v[200:203], 0
	v_mfma_f32_16x16x32_bf16 v[30:33], v[148:151], v[200:203], 0
	v_mfma_f32_16x16x32_bf16 v[10:13], v[130:133], v[208:211], 0
	v_mfma_f32_16x16x32_bf16 v[14:17], v[148:151], v[208:211], 0
	s_setprio 0
	s_setprio 1
	v_mfma_f32_16x16x32_bf16 v[58:61], v[144:147], v[186:189], v[58:61]
	v_mfma_f32_16x16x32_bf16 v[62:65], v[152:155], v[186:189], v[62:65]
	v_mfma_f32_16x16x32_bf16 v[42:45], v[144:147], v[196:199], v[42:45]
	v_mfma_f32_16x16x32_bf16 v[46:49], v[152:155], v[196:199], v[46:49]
	v_mfma_f32_16x16x32_bf16 v[26:29], v[144:147], v[204:207], v[26:29]
	v_mfma_f32_16x16x32_bf16 v[30:33], v[152:155], v[204:207], v[30:33]
	v_mfma_f32_16x16x32_bf16 v[10:13], v[144:147], v[212:215], v[10:13]
	v_mfma_f32_16x16x32_bf16 v[14:17], v[152:155], v[212:215], v[14:17]
	s_setprio 0
	s_setprio 1
	v_mfma_f32_16x16x32_bf16 v[50:53], v[156:159], v[182:185], 0
	v_mfma_f32_16x16x32_bf16 v[54:57], v[168:171], v[182:185], 0
	v_mfma_f32_16x16x32_bf16 v[34:37], v[156:159], v[190:193], 0
	v_mfma_f32_16x16x32_bf16 v[38:41], v[168:171], v[190:193], 0
	v_mfma_f32_16x16x32_bf16 v[18:21], v[156:159], v[200:203], 0
	v_mfma_f32_16x16x32_bf16 v[22:25], v[168:171], v[200:203], 0
	v_mfma_f32_16x16x32_bf16 v[6:9], v[156:159], v[208:211], 0
	v_mfma_f32_16x16x32_bf16 v[2:5], v[168:171], v[208:211], 0
	s_setprio 0
	s_setprio 1
	v_mfma_f32_16x16x32_bf16 v[50:53], v[160:163], v[186:189], v[50:53]
	v_mfma_f32_16x16x32_bf16 v[54:57], v[178:181], v[186:189], v[54:57]
	v_mfma_f32_16x16x32_bf16 v[34:37], v[160:163], v[196:199], v[34:37]
	v_mfma_f32_16x16x32_bf16 v[38:41], v[178:181], v[196:199], v[38:41]
	v_mfma_f32_16x16x32_bf16 v[18:21], v[160:163], v[204:207], v[18:21]
	v_mfma_f32_16x16x32_bf16 v[22:25], v[178:181], v[204:207], v[22:25]
	v_mfma_f32_16x16x32_bf16 v[6:9], v[160:163], v[212:215], v[6:9]
	v_mfma_f32_16x16x32_bf16 v[2:5], v[178:181], v[212:215], v[2:5]
	s_setprio 0
	s_barrier
	s_add_i32 s37, 0, 0x18000
	v_add_u32_e32 v0, s37, v174
	s_add_i32 s42, 0, 0x1c000
	ds_read_b128 v[130:133], v0
	ds_read_b128 v[144:147], v0 offset:1024
	ds_read_b128 v[148:151], v0 offset:2048
	ds_read_b128 v[152:155], v0 offset:3072
	v_add_u32_e32 v0, s42, v174
	ds_read_b128 v[156:159], v0
	ds_read_b128 v[160:163], v0 offset:1024
	ds_read_b128 v[168:171], v0 offset:2048
	ds_read_b128 v[178:181], v0 offset:3072
	s_add_u32 s20, s20, s18
	s_addc_u32 s21, s21, 0
	s_mov_b32 m0, s72
	v_lshl_add_u64 v[226:227], s[20:21], 0, v[134:135]
	ds_read_b128 v[182:185], v177 offset:32768
	ds_read_b128 v[186:189], v177 offset:33792
	ds_read_b128 v[190:193], v177 offset:34816
	ds_read_b128 v[196:199], v177 offset:35840
	ds_read_b128 v[200:203], v177 offset:36864
	ds_read_b128 v[204:207], v177 offset:37888
	ds_read_b128 v[208:211], v177 offset:38912
	ds_read_b128 v[212:215], v177 offset:39936
	global_load_lds_dwordx4 v[226:227], off
	v_lshl_add_u64 v[226:227], s[20:21], 0, v[136:137]
	s_mov_b32 m0, s73
	s_nop 0
	global_load_lds_dwordx4 v[226:227], off
	s_waitcnt vmcnt(8)
	s_waitcnt lgkmcnt(0)
	s_barrier
	s_setprio 1
	s_waitcnt lgkmcnt(0)
	v_mfma_f32_16x16x32_bf16 v[122:125], v[130:133], v[182:185], v[122:125]
	v_mfma_f32_16x16x32_bf16 v[126:129], v[148:151], v[182:185], v[126:129]
	v_lshl_add_u64 v[164:165], v[164:165], 0, s[48:49]
	v_mfma_f32_16x16x32_bf16 v[106:109], v[130:133], v[190:193], v[106:109]
	v_mfma_f32_16x16x32_bf16 v[110:113], v[148:151], v[190:193], v[110:113]
	v_lshl_add_u64 v[216:217], v[216:217], 0, s[48:49]
	v_mfma_f32_16x16x32_bf16 v[90:93], v[130:133], v[200:203], v[90:93]
	v_mfma_f32_16x16x32_bf16 v[94:97], v[148:151], v[200:203], v[94:97]
	v_lshl_add_u64 v[218:219], v[218:219], 0, s[48:49]
	v_mfma_f32_16x16x32_bf16 v[74:77], v[130:133], v[208:211], v[74:77]
	v_mfma_f32_16x16x32_bf16 v[78:81], v[148:151], v[208:211], v[78:81]
	v_lshl_add_u64 v[220:221], v[220:221], 0, s[48:49]
	s_setprio 0
	s_setprio 1
	v_mfma_f32_16x16x32_bf16 v[122:125], v[144:147], v[186:189], v[122:125]
	v_mfma_f32_16x16x32_bf16 v[126:129], v[152:155], v[186:189], v[126:129]
	v_lshl_add_u64 v[222:223], v[222:223], 0, s[48:49]
	v_mfma_f32_16x16x32_bf16 v[106:109], v[144:147], v[196:199], v[106:109]
	v_mfma_f32_16x16x32_bf16 v[110:113], v[152:155], v[196:199], v[110:113]
	v_lshl_add_u64 v[224:225], v[224:225], 0, s[48:49]
	v_mfma_f32_16x16x32_bf16 v[90:93], v[144:147], v[204:207], v[90:93]
	v_mfma_f32_16x16x32_bf16 v[94:97], v[152:155], v[204:207], v[94:97]
	v_mfma_f32_16x16x32_bf16 v[74:77], v[144:147], v[212:215], v[74:77]
	v_mfma_f32_16x16x32_bf16 v[78:81], v[152:155], v[212:215], v[78:81]
	s_setprio 0
	s_setprio 1
	v_mfma_f32_16x16x32_bf16 v[114:117], v[156:159], v[182:185], v[114:117]
	v_mfma_f32_16x16x32_bf16 v[118:121], v[168:171], v[182:185], v[118:121]
	v_mfma_f32_16x16x32_bf16 v[98:101], v[156:159], v[190:193], v[98:101]
	v_mfma_f32_16x16x32_bf16 v[102:105], v[168:171], v[190:193], v[102:105]
	v_mfma_f32_16x16x32_bf16 v[82:85], v[156:159], v[200:203], v[82:85]
	v_mfma_f32_16x16x32_bf16 v[86:89], v[168:171], v[200:203], v[86:89]
	v_mfma_f32_16x16x32_bf16 v[66:69], v[156:159], v[208:211], v[66:69]
	v_mfma_f32_16x16x32_bf16 v[70:73], v[168:171], v[208:211], v[70:73]
	s_setprio 0
	s_setprio 1
	v_mfma_f32_16x16x32_bf16 v[114:117], v[160:163], v[186:189], v[114:117]
	v_mfma_f32_16x16x32_bf16 v[118:121], v[178:181], v[186:189], v[118:121]
	v_mfma_f32_16x16x32_bf16 v[98:101], v[160:163], v[196:199], v[98:101]
	v_mfma_f32_16x16x32_bf16 v[102:105], v[178:181], v[196:199], v[102:105]
	v_mfma_f32_16x16x32_bf16 v[82:85], v[160:163], v[204:207], v[82:85]
	v_mfma_f32_16x16x32_bf16 v[86:89], v[178:181], v[204:207], v[86:89]
	v_mfma_f32_16x16x32_bf16 v[66:69], v[160:163], v[212:215], v[66:69]
	v_mfma_f32_16x16x32_bf16 v[70:73], v[178:181], v[212:215], v[70:73]
	s_setprio 0
	s_barrier
; #define PG8_STAGE(bufoff, gbase, voff) do { _Pragma("unroll") for (int _i = 0; _i < 2; ++_i) \
;         __builtin_amdgcn_global_load_lds((const unsigned*)((const char*)(gbase) + (voff)[_i]), (LAS unsigned*)(lds + (bufoff) + ldsw + _i * 8192), 16, 0, 0); } while (0)
; #define PG8_LDA(dst, b, h) do { _Pragma("unroll") for (int m = 0; m < 4; ++m) _Pragma("unroll") for (int k = 0; k < 2; ++k) dst[m][k] = *(const LAS bf16x8*)(lds + PG8_SA(b, h) + aoff + m * 2048 + k * 1024); } while (0)
; #define PG8_LDB(dst, b, h) do { _Pragma("unroll") for (int n = 0; n < 2; ++n) _Pragma("unroll") for (int k = 0; k < 2; ++k) dst[n][k] = *(const LAS bf16x8*)(lds + PG8_SB(b, h) + boff + n * 2048 + k * 1024); } while (0)
; #define PG8_MMA(ai, bj, At, Bt) do { __builtin_amdgcn_s_setprio(1); _Pragma("unroll") for (int m = 0; m < 4; ++m) _Pragma("unroll") for (int n = 0; n < 2; ++n) _Pragma("unroll") for (int k = 0; k < 2; ++k) \
;         acc[ai][bj][m][n] = __builtin_amdgcn_mfma_f32_16x16x32_bf16(Bt[n][k], At[m][k], acc[ai][bj][m][n], 0, 0, 0); __builtin_amdgcn_s_setprio(0); } while (0)
; #define PG8_WAIT_V(n) asm volatile("s_waitcnt vmcnt(" #n ")" ::: "memory")
; template <bool PERM>
; __device__ __forceinline__ void gemm_phase(LAS unsigned char* lds, const Gemm g, const Sched& S, const EpiDesc& E, const Ctx& C) {
;     ...
;             PG8_LDB(B0, 0, 0); PG8_LDB(B1, 0, 1); PG8_SCHED; PG8_LDA(At, 0, 0); PG8_STAGE(PG8_SA(1, 1), a1 + hstepA, voffA);
;             PG8_WAIT_V(8); PG8_WAIT_L(0); PG8_BAR; PG8_MMA(0, 0, At, B0); PG8_MMA(0, 1, At, B1); PG8_BAR; PG8_SCHED;
;             PG8_LDA(At, 0, 1); PG8_STAGE(PG8_SB(0, 0), b2, voffB); PG8_STAGE(PG8_SB(0, 1), b2 + hstepB, voffB); PG8_STAGE(PG8_SA(0, 0), a2, voffA);
;             PG8_WAIT_V(8); PG8_WAIT_L(0); PG8_BAR; PG8_MMA(1, 0, At, B0); PG8_MMA(1, 1, At, B1); PG8_BAR; PG8_SCHED;
;             PG8_LDB(B0, 1, 0); PG8_LDB(B1, 1, 1); PG8_SCHED; PG8_LDA(At, 1, 0); PG8_STAGE(PG8_SA(0, 1), a2 + hstepA, voffA);
;             PG8_WAIT_V(8); PG8_WAIT_L(0); PG8_BAR; PG8_MMA(0, 0, At, B0); PG8_MMA(0, 1, At, B1); PG8_BAR; PG8_SCHED;
;             PG8_LDA(At, 1, 1); PG8_STAGE(PG8_SB(1, 0), b3, voffB); PG8_STAGE(PG8_SB(1, 1), b3 + hstepB, voffB); PG8_STAGE(PG8_SA(1, 0), a3, voffA);
;             PG8_WAIT_V(8); PG8_WAIT_L(0); PG8_BAR; PG8_MMA(1, 0, At, B0); PG8_MMA(1, 1, At, B1); PG8_BAR; PG8_SCHED;
;         }
	s_add_i32 s20, s37, s69
	s_mov_b32 m0, s20
	ds_read_b128 v[182:185], v177 offset:49152
	ds_read_b128 v[186:189], v177 offset:50176
	ds_read_b128 v[190:193], v177 offset:51200
	ds_read_b128 v[196:199], v177 offset:52224
	ds_read_b128 v[200:203], v177 offset:53248
	ds_read_b128 v[204:207], v177 offset:54272
	ds_read_b128 v[208:211], v177 offset:55296
	ds_read_b128 v[212:215], v177 offset:56320
	global_load_lds_dwordx4 v[164:165], off
	s_add_i32 m0, s20, 0x2000
	s_add_i32 s20, s42, s69
	global_load_lds_dwordx4 v[216:217], off
	s_mov_b32 m0, s20
	s_nop 0
	global_load_lds_dwordx4 v[218:219], off
	s_add_i32 m0, s20, 0x2000
	s_nop 0
	global_load_lds_dwordx4 v[220:221], off
	s_mov_b32 m0, s75
	s_nop 0
	global_load_lds_dwordx4 v[222:223], off
	s_mov_b32 m0, s76
	s_nop 0
	global_load_lds_dwordx4 v[224:225], off
	s_waitcnt vmcnt(8)
	s_waitcnt lgkmcnt(0)
	s_barrier
	s_setprio 1
	s_waitcnt lgkmcnt(0)
	v_mfma_f32_16x16x32_bf16 v[58:61], v[130:133], v[182:185], v[58:61]
	v_mfma_f32_16x16x32_bf16 v[62:65], v[148:151], v[182:185], v[62:65]
	v_mfma_f32_16x16x32_bf16 v[42:45], v[130:133], v[190:193], v[42:45]
	v_mfma_f32_16x16x32_bf16 v[46:49], v[148:151], v[190:193], v[46:49]
	v_mfma_f32_16x16x32_bf16 v[26:29], v[130:133], v[200:203], v[26:29]
	v_mfma_f32_16x16x32_bf16 v[30:33], v[148:151], v[200:203], v[30:33]
	v_mfma_f32_16x16x32_bf16 v[10:13], v[130:133], v[208:211], v[10:13]
	v_mfma_f32_16x16x32_bf16 v[14:17], v[148:151], v[208:211], v[14:17]
	s_setprio 0
	s_setprio 1
	v_mfma_f32_16x16x32_bf16 v[58:61], v[144:147], v[186:189], v[58:61]
	v_mfma_f32_16x16x32_bf16 v[62:65], v[152:155], v[186:189], v[62:65]
	v_mfma_f32_16x16x32_bf16 v[42:45], v[144:147], v[196:199], v[42:45]
	v_mfma_f32_16x16x32_bf16 v[46:49], v[152:155], v[196:199], v[46:49]
	v_mfma_f32_16x16x32_bf16 v[26:29], v[144:147], v[204:207], v[26:29]
	v_mfma_f32_16x16x32_bf16 v[30:33], v[152:155], v[204:207], v[30:33]
	v_mfma_f32_16x16x32_bf16 v[10:13], v[144:147], v[212:215], v[10:13]
	v_mfma_f32_16x16x32_bf16 v[14:17], v[152:155], v[212:215], v[14:17]
	s_setprio 0
	s_setprio 1
	v_mfma_f32_16x16x32_bf16 v[50:53], v[156:159], v[182:185], v[50:53]
	v_mfma_f32_16x16x32_bf16 v[54:57], v[168:171], v[182:185], v[54:57]
	v_mfma_f32_16x16x32_bf16 v[34:37], v[156:159], v[190:193], v[34:37]
	v_mfma_f32_16x16x32_bf16 v[38:41], v[168:171], v[190:193], v[38:41]
	v_mfma_f32_16x16x32_bf16 v[18:21], v[156:159], v[200:203], v[18:21]
	v_mfma_f32_16x16x32_bf16 v[22:25], v[168:171], v[200:203], v[22:25]
	v_mfma_f32_16x16x32_bf16 v[6:9], v[156:159], v[208:211], v[6:9]
	v_mfma_f32_16x16x32_bf16 v[2:5], v[168:171], v[208:211], v[2:5]
	s_setprio 0
	s_setprio 1
	v_mfma_f32_16x16x32_bf16 v[50:53], v[160:163], v[186:189], v[50:53]
	v_mfma_f32_16x16x32_bf16 v[54:57], v[178:181], v[186:189], v[54:57]
	v_mfma_f32_16x16x32_bf16 v[34:37], v[160:163], v[196:199], v[34:37]
	v_mfma_f32_16x16x32_bf16 v[38:41], v[178:181], v[196:199], v[38:41]
	v_mfma_f32_16x16x32_bf16 v[18:21], v[160:163], v[204:207], v[18:21]
	v_mfma_f32_16x16x32_bf16 v[22:25], v[178:181], v[204:207], v[22:25]
	v_mfma_f32_16x16x32_bf16 v[6:9], v[160:163], v[212:215], v[6:9]
	v_mfma_f32_16x16x32_bf16 v[2:5], v[178:181], v[212:215], v[2:5]
	s_setprio 0
	s_barrier
	s_add_u32 s2, s2, 0x100
	s_addc_u32 s3, s3, 0
	s_add_u32 s23, s23, 0x100
	s_addc_u32 s29, s29, 0
	s_cmp_ge_i32 s36, s28
	s_mov_b32 s20, s36
	s_cbranch_scc1 .Lkb_exit
.LBB0_241:
	s_add_i32 s36, s20, 2
	s_add_u32 s37, s2, 0x80
	s_addc_u32 s21, s3, 0
	s_add_i32 s44, 0, 0x10000
	s_cmp_eq_u32 s22, s20
	s_cselect_b32 s21, s63, s21
	s_cselect_b32 s20, s62, s37
	v_add_u32_e32 v0, s44, v174
	s_cselect_b32 s43, s65, s29
	s_cselect_b32 s42, s64, s23
	s_add_i32 s37, 0, 0x14000
	s_waitcnt lgkmcnt(0)
	ds_read_b128 v[130:133], v0
	ds_read_b128 v[144:147], v0 offset:1024
	ds_read_b128 v[148:151], v0 offset:2048
	ds_read_b128 v[152:155], v0 offset:3072
	v_add_u32_e32 v0, s37, v174
	ds_read_b128 v[156:159], v0
	ds_read_b128 v[160:163], v0 offset:1024
	ds_read_b128 v[168:171], v0 offset:2048
	ds_read_b128 v[178:181], v0 offset:3072
	v_lshl_add_u64 v[164:165], s[2:3], 0, v[140:141]
	s_add_i32 m0, s70, 0xc000
	ds_read_b128 v[182:185], v177
	ds_read_b128 v[186:189], v177 offset:1024
	ds_read_b128 v[190:193], v177 offset:2048
	ds_read_b128 v[196:199], v177 offset:3072
	ds_read_b128 v[200:203], v177 offset:4096
	ds_read_b128 v[204:207], v177 offset:5120
	ds_read_b128 v[208:211], v177 offset:6144
	ds_read_b128 v[212:215], v177 offset:7168
	global_load_lds_dwordx4 v[164:165], off
	v_lshl_add_u64 v[164:165], s[2:3], 0, v[142:143]
	s_add_i32 m0, s70, 0xe000
	s_nop 0
	global_load_lds_dwordx4 v[164:165], off
	s_waitcnt vmcnt(8)
	s_waitcnt lgkmcnt(0)
	s_barrier
; #define PG8_STAGE(bufoff, gbase, voff) do { _Pragma("unroll") for (int _i = 0; _i < 2; ++_i) \
;         __builtin_amdgcn_global_load_lds((const unsigned*)((const char*)(gbase) + (voff)[_i]), (LAS unsigned*)(lds + (bufoff) + ldsw + _i * 8192), 16, 0, 0); } while (0)
; #define PG8_LDA(dst, b, h) do { _Pragma("unroll") for (int m = 0; m < 4; ++m) _Pragma("unroll") for (int k = 0; k < 2; ++k) dst[m][k] = *(const LAS bf16x8*)(lds + PG8_SA(b, h) + aoff + m * 2048 + k * 1024); } while (0)
; #define PG8_LDB(dst, b, h) do { _Pragma("unroll") for (int n = 0; n < 2; ++n) _Pragma("unroll") for (int k = 0; k < 2; ++k) dst[n][k] = *(const LAS bf16x8*)(lds + PG8_SB(b, h) + boff + n * 2048 + k * 1024); } while (0)
; #define PG8_MMA(ai, bj, At, Bt) do { __builtin_amdgcn_s_setprio(1); _Pragma("unroll") for (int m = 0; m < 4; ++m) _Pragma("unroll") for (int n = 0; n < 2; ++n) _Pragma("unroll") for (int k = 0; k < 2; ++k) \
;         acc[ai][bj][m][n] = __builtin_amdgcn_mfma_f32_16x16x32_bf16(Bt[n][k], At[m][k], acc[ai][bj][m][n], 0, 0, 0); __builtin_amdgcn_s_setprio(0); } while (0)
; #define PG8_WAIT_V(n) asm volatile("s_waitcnt vmcnt(" #n ")" ::: "memory")
; #define PG8_BAR __builtin_amdgcn_s_barrier()
; template <bool PERM>
; __device__ __forceinline__ void gemm_phase(LAS unsigned char* lds, const Gemm g, const Sched& S, const EpiDesc& E, const Ctx& C) {
;     ...
;             PG8_LDB(B0, 0, 0); PG8_LDB(B1, 0, 1); PG8_SCHED; PG8_LDA(At, 0, 0); PG8_STAGE(PG8_SA(1, 1), a1 + hstepA, voffA);
;             PG8_WAIT_V(8); PG8_WAIT_L(0); PG8_BAR; PG8_MMA(0, 0, At, B0); PG8_MMA(0, 1, At, B1); PG8_BAR; PG8_SCHED;
;             PG8_LDA(At, 0, 1); PG8_STAGE(PG8_SB(0, 0), b2, voffB); PG8_STAGE(PG8_SB(0, 1), b2 + hstepB, voffB); PG8_STAGE(PG8_SA(0, 0), a2, voffA);
;             PG8_WAIT_V(8); PG8_WAIT_L(0); PG8_BAR; PG8_MMA(1, 0, At, B0); PG8_MMA(1, 1, At, B1); PG8_BAR; PG8_SCHED;
;             PG8_LDB(B0, 1, 0); PG8_LDB(B1, 1, 1); PG8_SCHED; PG8_LDA(At, 1, 0); PG8_STAGE(PG8_SA(0, 1), a2 + hstepA, voffA);
;             PG8_WAIT_V(8); PG8_WAIT_L(0); PG8_BAR; PG8_MMA(0, 0, At, B0); PG8_MMA(0, 1, At, B1); PG8_BAR; PG8_SCHED;
;             PG8_LDA(At, 1, 1); PG8_STAGE(PG8_SB(1, 0), b3, voffB); PG8_STAGE(PG8_SB(1, 1), b3 + hstepB, voffB); PG8_STAGE(PG8_SA(1, 0), a3, voffA);
;             PG8_WAIT_V(8); PG8_WAIT_L(0); PG8_BAR; PG8_MMA(1, 0, At, B0); PG8_MMA(1, 1, At, B1); PG8_BAR; PG8_SCHED;
	s_setprio 1
	s_waitcnt lgkmcnt(0)
	v_mfma_f32_16x16x32_bf16 v[122:125], v[130:133], v[182:185], v[122:125]
	v_mfma_f32_16x16x32_bf16 v[126:129], v[148:151], v[182:185], v[126:129]
	v_lshl_add_u64 v[164:165], s[42:43], 0, v[134:135]
	v_mfma_f32_16x16x32_bf16 v[106:109], v[130:133], v[190:193], v[106:109]
	v_mfma_f32_16x16x32_bf16 v[110:113], v[148:151], v[190:193], v[110:113]
	v_lshl_add_u64 v[216:217], s[42:43], 0, v[136:137]
	v_mfma_f32_16x16x32_bf16 v[90:93], v[130:133], v[200:203], v[90:93]
	v_mfma_f32_16x16x32_bf16 v[94:97], v[148:151], v[200:203], v[94:97]
	s_add_u32 s42, s42, s18
	s_addc_u32 s43, s43, 0
	v_mfma_f32_16x16x32_bf16 v[74:77], v[130:133], v[208:211], v[74:77]
	v_mfma_f32_16x16x32_bf16 v[78:81], v[148:151], v[208:211], v[78:81]
	v_lshl_add_u64 v[218:219], s[42:43], 0, v[134:135]
	s_setprio 0
	s_setprio 1
	v_mfma_f32_16x16x32_bf16 v[122:125], v[144:147], v[186:189], v[122:125]
	v_mfma_f32_16x16x32_bf16 v[126:129], v[152:155], v[186:189], v[126:129]
	v_lshl_add_u64 v[220:221], s[42:43], 0, v[136:137]
	v_mfma_f32_16x16x32_bf16 v[106:109], v[144:147], v[196:199], v[106:109]
	v_mfma_f32_16x16x32_bf16 v[110:113], v[152:155], v[196:199], v[110:113]
	v_lshl_add_u64 v[222:223], s[20:21], 0, v[134:135]
	v_mfma_f32_16x16x32_bf16 v[90:93], v[144:147], v[204:207], v[90:93]
	v_mfma_f32_16x16x32_bf16 v[94:97], v[152:155], v[204:207], v[94:97]
	v_lshl_add_u64 v[224:225], s[20:21], 0, v[136:137]
	v_mfma_f32_16x16x32_bf16 v[74:77], v[144:147], v[212:215], v[74:77]
	v_mfma_f32_16x16x32_bf16 v[78:81], v[152:155], v[212:215], v[78:81]
	s_setprio 0
	s_setprio 1
	v_mfma_f32_16x16x32_bf16 v[114:117], v[156:159], v[182:185], v[114:117]
	v_mfma_f32_16x16x32_bf16 v[118:121], v[168:171], v[182:185], v[118:121]
	v_mfma_f32_16x16x32_bf16 v[98:101], v[156:159], v[190:193], v[98:101]
	v_mfma_f32_16x16x32_bf16 v[102:105], v[168:171], v[190:193], v[102:105]
	v_mfma_f32_16x16x32_bf16 v[82:85], v[156:159], v[200:203], v[82:85]
	v_mfma_f32_16x16x32_bf16 v[86:89], v[168:171], v[200:203], v[86:89]
	v_mfma_f32_16x16x32_bf16 v[66:69], v[156:159], v[208:211], v[66:69]
	v_mfma_f32_16x16x32_bf16 v[70:73], v[168:171], v[208:211], v[70:73]
	s_setprio 0
	s_setprio 1
	v_mfma_f32_16x16x32_bf16 v[114:117], v[160:163], v[186:189], v[114:117]
	v_mfma_f32_16x16x32_bf16 v[118:121], v[178:181], v[186:189], v[118:121]
	v_mfma_f32_16x16x32_bf16 v[98:101], v[160:163], v[196:199], v[98:101]
	v_mfma_f32_16x16x32_bf16 v[102:105], v[178:181], v[196:199], v[102:105]
	v_mfma_f32_16x16x32_bf16 v[82:85], v[160:163], v[204:207], v[82:85]
	v_mfma_f32_16x16x32_bf16 v[86:89], v[178:181], v[204:207], v[86:89]
	v_mfma_f32_16x16x32_bf16 v[66:69], v[160:163], v[212:215], v[66:69]
	v_mfma_f32_16x16x32_bf16 v[70:73], v[178:181], v[212:215], v[70:73]
	s_setprio 0
	s_barrier
	s_add_i32 s44, s44, s69
	s_mov_b32 m0, s44
	ds_read_b128 v[182:185], v177 offset:16384
	ds_read_b128 v[186:189], v177 offset:17408
	ds_read_b128 v[190:193], v177 offset:18432
	ds_read_b128 v[196:199], v177 offset:19456
	ds_read_b128 v[200:203], v177 offset:20480
	ds_read_b128 v[204:207], v177 offset:21504
	ds_read_b128 v[208:211], v177 offset:22528
	ds_read_b128 v[212:215], v177 offset:23552
	global_load_lds_dwordx4 v[164:165], off
	s_add_i32 m0, s44, 0x2000
	s_add_i32 s37, s37, s69
	global_load_lds_dwordx4 v[216:217], off
	s_mov_b32 m0, s37
	s_nop 0
	global_load_lds_dwordx4 v[218:219], off
	s_add_i32 m0, s37, 0x2000
	s_nop 0
	global_load_lds_dwordx4 v[220:221], off
	s_mov_b32 m0, s70
	s_nop 0
	global_load_lds_dwordx4 v[222:223], off
	s_mov_b32 m0, s71
	s_nop 0
	global_load_lds_dwordx4 v[224:225], off
	s_waitcnt vmcnt(8)
	s_waitcnt lgkmcnt(0)
	s_barrier
	s_setprio 1
	s_waitcnt lgkmcnt(0)
	v_mfma_f32_16x16x32_bf16 v[58:61], v[130:133], v[182:185], v[58:61]
	v_mfma_f32_16x16x32_bf16 v[62:65], v[148:151], v[182:185], v[62:65]
	v_mfma_f32_16x16x32_bf16 v[42:45], v[130:133], v[190:193], v[42:45]
	v_mfma_f32_16x16x32_bf16 v[46:49], v[148:151], v[190:193], v[46:49]
	v_mfma_f32_16x16x32_bf16 v[26:29], v[130:133], v[200:203], v[26:29]
	v_mfma_f32_16x16x32_bf16 v[30:33], v[148:151], v[200:203], v[30:33]
	v_mfma_f32_16x16x32_bf16 v[10:13], v[130:133], v[208:211], v[10:13]
	v_mfma_f32_16x16x32_bf16 v[14:17], v[148:151], v[208:211], v[14:17]
	s_setprio 0
	s_setprio 1
	v_mfma_f32_16x16x32_bf16 v[58:61], v[144:147], v[186:189], v[58:61]
	v_mfma_f32_16x16x32_bf16 v[62:65], v[152:155], v[186:189], v[62:65]
	v_mfma_f32_16x16x32_bf16 v[42:45], v[144:147], v[196:199], v[42:45]
	v_mfma_f32_16x16x32_bf16 v[46:49], v[152:155], v[196:199], v[46:49]
	v_mfma_f32_16x16x32_bf16 v[26:29], v[144:147], v[204:207], v[26:29]
	v_mfma_f32_16x16x32_bf16 v[30:33], v[152:155], v[204:207], v[30:33]
	v_mfma_f32_16x16x32_bf16 v[10:13], v[144:147], v[212:215], v[10:13]
	v_mfma_f32_16x16x32_bf16 v[14:17], v[152:155], v[212:215], v[14:17]
	s_setprio 0
	s_setprio 1
	v_mfma_f32_16x16x32_bf16 v[50:53], v[156:159], v[182:185], v[50:53]
	v_mfma_f32_16x16x32_bf16 v[54:57], v[168:171], v[182:185], v[54:57]
	v_mfma_f32_16x16x32_bf16 v[34:37], v[156:159], v[190:193], v[34:37]
	v_mfma_f32_16x16x32_bf16 v[38:41], v[168:171], v[190:193], v[38:41]
	v_mfma_f32_16x16x32_bf16 v[18:21], v[156:159], v[200:203], v[18:21]
	v_mfma_f32_16x16x32_bf16 v[22:25], v[168:171], v[200:203], v[22:25]
	v_mfma_f32_16x16x32_bf16 v[6:9], v[156:159], v[208:211], v[6:9]
	v_mfma_f32_16x16x32_bf16 v[2:5], v[168:171], v[208:211], v[2:5]
	s_setprio 0
	s_setprio 1
	v_mfma_f32_16x16x32_bf16 v[50:53], v[160:163], v[186:189], v[50:53]
	v_mfma_f32_16x16x32_bf16 v[54:57], v[178:181], v[186:189], v[54:57]
	v_mfma_f32_16x16x32_bf16 v[34:37], v[160:163], v[196:199], v[34:37]
	v_mfma_f32_16x16x32_bf16 v[38:41], v[178:181], v[196:199], v[38:41]
	v_mfma_f32_16x16x32_bf16 v[18:21], v[160:163], v[204:207], v[18:21]
	v_mfma_f32_16x16x32_bf16 v[22:25], v[178:181], v[204:207], v[22:25]
	v_mfma_f32_16x16x32_bf16 v[6:9], v[160:163], v[212:215], v[6:9]
	v_mfma_f32_16x16x32_bf16 v[2:5], v[178:181], v[212:215], v[2:5]
	s_setprio 0
	s_barrier
; #define PG8_STAGE(bufoff, gbase, voff) do { _Pragma("unroll") for (int _i = 0; _i < 2; ++_i) \
;         __builtin_amdgcn_global_load_lds((const unsigned*)((const char*)(gbase) + (voff)[_i]), (LAS unsigned*)(lds + (bufoff) + ldsw + _i * 8192), 16, 0, 0); } while (0)
; #define PG8_LDA(dst, b, h) do { _Pragma("unroll") for (int m = 0; m < 4; ++m) _Pragma("unroll") for (int k = 0; k < 2; ++k) dst[m][k] = *(const LAS bf16x8*)(lds + PG8_SA(b, h) + aoff + m * 2048 + k * 1024); } while (0)
; #define PG8_LDB(dst, b, h) do { _Pragma("unroll") for (int n = 0; n < 2; ++n) _Pragma("unroll") for (int k = 0; k < 2; ++k) dst[n][k] = *(const LAS bf16x8*)(lds + PG8_SB(b, h) + boff + n * 2048 + k * 1024); } while (0)
; #define PG8_MMA(ai, bj, At, Bt) do { __builtin_amdgcn_s_setprio(1); _Pragma("unroll") for (int m = 0; m < 4; ++m) _Pragma("unroll") for (int n = 0; n < 2; ++n) _Pragma("unroll") for (int k = 0; k < 2; ++k) \
;         acc[ai][bj][m][n] = __builtin_amdgcn_mfma_f32_16x16x32_bf16(Bt[n][k], At[m][k], acc[ai][bj][m][n], 0, 0, 0); __builtin_amdgcn_s_setprio(0); } while (0)
; #define PG8_WAIT_V(n) asm volatile("s_waitcnt vmcnt(" #n ")" ::: "memory")
; #define PG8_WAIT_L(n) asm volatile("s_waitcnt lgkmcnt(" #n ")" ::: "memory")
; #define PG8_BAR __builtin_amdgcn_s_barrier()
; #define PG8_SCHED __builtin_amdgcn_sched_barrier(0)
; template <bool PERM>
; __device__ __forceinline__ void gemm_phase(LAS unsigned char* lds, const Gemm g, const Sched& S, const EpiDesc& E, const Ctx& C) {
;     ...
;             PG8_LDB(B0, 1, 0); PG8_LDB(B1, 1, 1); PG8_SCHED; PG8_LDA(At, 1, 0); PG8_STAGE(PG8_SA(0, 1), a2 + hstepA, voffA);
;             PG8_WAIT_V(8); PG8_WAIT_L(0); PG8_BAR; PG8_MMA(0, 0, At, B0); PG8_MMA(0, 1, At, B1); PG8_BAR; PG8_SCHED;
;             PG8_LDA(At, 1, 1); PG8_STAGE(PG8_SB(1, 0), b3, voffB); PG8_STAGE(PG8_SB(1, 1), b3 + hstepB, voffB); PG8_STAGE(PG8_SA(1, 0), a3, voffA);
;             PG8_WAIT_V(8); PG8_WAIT_L(0); PG8_BAR; PG8_MMA(1, 0, At, B0); PG8_MMA(1, 1, At, B1); PG8_BAR; PG8_SCHED;
	s_add_i32 s37, 0, 0x18000
	v_add_u32_e32 v0, s37, v174
	s_add_i32 s42, 0, 0x1c000
	ds_read_b128 v[130:133], v0
	ds_read_b128 v[144:147], v0 offset:1024
	ds_read_b128 v[148:151], v0 offset:2048
	ds_read_b128 v[152:155], v0 offset:3072
	v_add_u32_e32 v0, s42, v174
	ds_read_b128 v[156:159], v0
	ds_read_b128 v[160:163], v0 offset:1024
	ds_read_b128 v[168:171], v0 offset:2048
	ds_read_b128 v[178:181], v0 offset:3072
	s_add_u32 s20, s20, s18
	s_addc_u32 s21, s21, 0
	s_mov_b32 m0, s72
	v_lshl_add_u64 v[226:227], s[20:21], 0, v[134:135]
	ds_read_b128 v[182:185], v177 offset:32768
	ds_read_b128 v[186:189], v177 offset:33792
	ds_read_b128 v[190:193], v177 offset:34816
	ds_read_b128 v[196:199], v177 offset:35840
	ds_read_b128 v[200:203], v177 offset:36864
	ds_read_b128 v[204:207], v177 offset:37888
	ds_read_b128 v[208:211], v177 offset:38912
	ds_read_b128 v[212:215], v177 offset:39936
	global_load_lds_dwordx4 v[226:227], off
	v_lshl_add_u64 v[226:227], s[20:21], 0, v[136:137]
	s_mov_b32 m0, s73
	s_nop 0
	global_load_lds_dwordx4 v[226:227], off
	s_waitcnt vmcnt(8)
	s_waitcnt lgkmcnt(0)
	s_barrier
	s_setprio 1
	s_waitcnt lgkmcnt(0)
	v_mfma_f32_16x16x32_bf16 v[122:125], v[130:133], v[182:185], v[122:125]
	v_mfma_f32_16x16x32_bf16 v[126:129], v[148:151], v[182:185], v[126:129]
	v_lshl_add_u64 v[164:165], v[164:165], 0, s[48:49]
	v_mfma_f32_16x16x32_bf16 v[106:109], v[130:133], v[190:193], v[106:109]
	v_mfma_f32_16x16x32_bf16 v[110:113], v[148:151], v[190:193], v[110:113]
	v_lshl_add_u64 v[216:217], v[216:217], 0, s[48:49]
	v_mfma_f32_16x16x32_bf16 v[90:93], v[130:133], v[200:203], v[90:93]
	v_mfma_f32_16x16x32_bf16 v[94:97], v[148:151], v[200:203], v[94:97]
	v_lshl_add_u64 v[218:219], v[218:219], 0, s[48:49]
	v_mfma_f32_16x16x32_bf16 v[74:77], v[130:133], v[208:211], v[74:77]
	v_mfma_f32_16x16x32_bf16 v[78:81], v[148:151], v[208:211], v[78:81]
	v_lshl_add_u64 v[220:221], v[220:221], 0, s[48:49]
	s_setprio 0
	s_setprio 1
	v_mfma_f32_16x16x32_bf16 v[122:125], v[144:147], v[186:189], v[122:125]
	v_mfma_f32_16x16x32_bf16 v[126:129], v[152:155], v[186:189], v[126:129]
	v_lshl_add_u64 v[222:223], v[222:223], 0, s[48:49]
	v_mfma_f32_16x16x32_bf16 v[106:109], v[144:147], v[196:199], v[106:109]
	v_mfma_f32_16x16x32_bf16 v[110:113], v[152:155], v[196:199], v[110:113]
	v_lshl_add_u64 v[224:225], v[224:225], 0, s[48:49]
	v_mfma_f32_16x16x32_bf16 v[90:93], v[144:147], v[204:207], v[90:93]
	v_mfma_f32_16x16x32_bf16 v[94:97], v[152:155], v[204:207], v[94:97]
	v_mfma_f32_16x16x32_bf16 v[74:77], v[144:147], v[212:215], v[74:77]
	v_mfma_f32_16x16x32_bf16 v[78:81], v[152:155], v[212:215], v[78:81]
	s_setprio 0
	s_setprio 1
	v_mfma_f32_16x16x32_bf16 v[114:117], v[156:159], v[182:185], v[114:117]
	v_mfma_f32_16x16x32_bf16 v[118:121], v[168:171], v[182:185], v[118:121]
	v_mfma_f32_16x16x32_bf16 v[98:101], v[156:159], v[190:193], v[98:101]
	v_mfma_f32_16x16x32_bf16 v[102:105], v[168:171], v[190:193], v[102:105]
	v_mfma_f32_16x16x32_bf16 v[82:85], v[156:159], v[200:203], v[82:85]
	v_mfma_f32_16x16x32_bf16 v[86:89], v[168:171], v[200:203], v[86:89]
	v_mfma_f32_16x16x32_bf16 v[66:69], v[156:159], v[208:211], v[66:69]
	v_mfma_f32_16x16x32_bf16 v[70:73], v[168:171], v[208:211], v[70:73]
	s_setprio 0
	s_setprio 1
	v_mfma_f32_16x16x32_bf16 v[114:117], v[160:163], v[186:189], v[114:117]
	v_mfma_f32_16x16x32_bf16 v[118:121], v[178:181], v[186:189], v[118:121]
	v_mfma_f32_16x16x32_bf16 v[98:101], v[160:163], v[196:199], v[98:101]
	v_mfma_f32_16x16x32_bf16 v[102:105], v[178:181], v[196:199], v[102:105]
	v_mfma_f32_16x16x32_bf16 v[82:85], v[160:163], v[204:207], v[82:85]
	v_mfma_f32_16x16x32_bf16 v[86:89], v[178:181], v[204:207], v[86:89]
	v_mfma_f32_16x16x32_bf16 v[66:69], v[160:163], v[212:215], v[66:69]
	v_mfma_f32_16x16x32_bf16 v[70:73], v[178:181], v[212:215], v[70:73]
	s_setprio 0
	s_barrier
; #define PG8_STAGE(bufoff, gbase, voff) do { _Pragma("unroll") for (int _i = 0; _i < 2; ++_i) \
;         __builtin_amdgcn_global_load_lds((const unsigned*)((const char*)(gbase) + (voff)[_i]), (LAS unsigned*)(lds + (bufoff) + ldsw + _i * 8192), 16, 0, 0); } while (0)
; #define PG8_LDA(dst, b, h) do { _Pragma("unroll") for (int m = 0; m < 4; ++m) _Pragma("unroll") for (int k = 0; k < 2; ++k) dst[m][k] = *(const LAS bf16x8*)(lds + PG8_SA(b, h) + aoff + m * 2048 + k * 1024); } while (0)
; #define PG8_MMA(ai, bj, At, Bt) do { __builtin_amdgcn_s_setprio(1); _Pragma("unroll") for (int m = 0; m < 4; ++m) _Pragma("unroll") for (int n = 0; n < 2; ++n) _Pragma("unroll") for (int k = 0; k < 2; ++k) \
;         acc[ai][bj][m][n] = __builtin_amdgcn_mfma_f32_16x16x32_bf16(Bt[n][k], At[m][k], acc[ai][bj][m][n], 0, 0, 0); __builtin_amdgcn_s_setprio(0); } while (0)
; #define PG8_WAIT_V(n) asm volatile("s_waitcnt vmcnt(" #n ")" ::: "memory")
; #define PG8_WAIT_L(n) asm volatile("s_waitcnt lgkmcnt(" #n ")" ::: "memory")
; #define PG8_BAR __builtin_amdgcn_s_barrier()
; #define PG8_SCHED __builtin_amdgcn_sched_barrier(0)
; template <bool PERM>
; __device__ __forceinline__ void gemm_phase(LAS unsigned char* lds, const Gemm g, const Sched& S, const EpiDesc& E, const Ctx& C) {
;     ...
;             PG8_LDA(At, 1, 1); PG8_STAGE(PG8_SB(1, 0), b3, voffB); PG8_STAGE(PG8_SB(1, 1), b3 + hstepB, voffB); PG8_STAGE(PG8_SA(1, 0), a3, voffA);
;             PG8_WAIT_V(8); PG8_WAIT_L(0); PG8_BAR; PG8_MMA(1, 0, At, B0); PG8_MMA(1, 1, At, B1); PG8_BAR; PG8_SCHED;
;         }
	s_add_i32 s20, s37, s69
	s_mov_b32 m0, s20
	ds_read_b128 v[182:185], v177 offset:49152
	ds_read_b128 v[186:189], v177 offset:50176
	ds_read_b128 v[190:193], v177 offset:51200
	ds_read_b128 v[196:199], v177 offset:52224
	ds_read_b128 v[200:203], v177 offset:53248
	ds_read_b128 v[204:207], v177 offset:54272
	ds_read_b128 v[208:211], v177 offset:55296
	ds_read_b128 v[212:215], v177 offset:56320
	global_load_lds_dwordx4 v[164:165], off
	s_add_i32 m0, s20, 0x2000
	s_add_i32 s20, s42, s69
	global_load_lds_dwordx4 v[216:217], off
	s_mov_b32 m0, s20
	s_nop 0
	global_load_lds_dwordx4 v[218:219], off
	s_add_i32 m0, s20, 0x2000
	s_nop 0
	global_load_lds_dwordx4 v[220:221], off
	s_mov_b32 m0, s75
	s_nop 0
	global_load_lds_dwordx4 v[222:223], off
	s_mov_b32 m0, s76
	s_nop 0
	global_load_lds_dwordx4 v[224:225], off
	s_waitcnt vmcnt(8)
	s_waitcnt lgkmcnt(0)
	s_barrier
	s_setprio 1
	s_waitcnt lgkmcnt(0)
	v_mfma_f32_16x16x32_bf16 v[58:61], v[130:133], v[182:185], v[58:61]
	v_mfma_f32_16x16x32_bf16 v[62:65], v[148:151], v[182:185], v[62:65]
	v_mfma_f32_16x16x32_bf16 v[42:45], v[130:133], v[190:193], v[42:45]
	v_mfma_f32_16x16x32_bf16 v[46:49], v[148:151], v[190:193], v[46:49]
	v_mfma_f32_16x16x32_bf16 v[26:29], v[130:133], v[200:203], v[26:29]
	v_mfma_f32_16x16x32_bf16 v[30:33], v[148:151], v[200:203], v[30:33]
	v_mfma_f32_16x16x32_bf16 v[10:13], v[130:133], v[208:211], v[10:13]
	v_mfma_f32_16x16x32_bf16 v[14:17], v[148:151], v[208:211], v[14:17]
	s_setprio 0
	s_setprio 1
	v_mfma_f32_16x16x32_bf16 v[58:61], v[144:147], v[186:189], v[58:61]
	v_mfma_f32_16x16x32_bf16 v[62:65], v[152:155], v[186:189], v[62:65]
	v_mfma_f32_16x16x32_bf16 v[42:45], v[144:147], v[196:199], v[42:45]
	v_mfma_f32_16x16x32_bf16 v[46:49], v[152:155], v[196:199], v[46:49]
	v_mfma_f32_16x16x32_bf16 v[26:29], v[144:147], v[204:207], v[26:29]
	v_mfma_f32_16x16x32_bf16 v[30:33], v[152:155], v[204:207], v[30:33]
	v_mfma_f32_16x16x32_bf16 v[10:13], v[144:147], v[212:215], v[10:13]
	v_mfma_f32_16x16x32_bf16 v[14:17], v[152:155], v[212:215], v[14:17]
	s_setprio 0
	s_setprio 1
	v_mfma_f32_16x16x32_bf16 v[50:53], v[156:159], v[182:185], v[50:53]
	v_mfma_f32_16x16x32_bf16 v[54:57], v[168:171], v[182:185], v[54:57]
	v_mfma_f32_16x16x32_bf16 v[34:37], v[156:159], v[190:193], v[34:37]
	v_mfma_f32_16x16x32_bf16 v[38:41], v[168:171], v[190:193], v[38:41]
	v_mfma_f32_16x16x32_bf16 v[18:21], v[156:159], v[200:203], v[18:21]
	v_mfma_f32_16x16x32_bf16 v[22:25], v[168:171], v[200:203], v[22:25]
	v_mfma_f32_16x16x32_bf16 v[6:9], v[156:159], v[208:211], v[6:9]
	v_mfma_f32_16x16x32_bf16 v[2:5], v[168:171], v[208:211], v[2:5]
	s_setprio 0
	s_setprio 1
	v_mfma_f32_16x16x32_bf16 v[50:53], v[160:163], v[186:189], v[50:53]
	v_mfma_f32_16x16x32_bf16 v[54:57], v[178:181], v[186:189], v[54:57]
	v_mfma_f32_16x16x32_bf16 v[34:37], v[160:163], v[196:199], v[34:37]
	v_mfma_f32_16x16x32_bf16 v[38:41], v[178:181], v[196:199], v[38:41]
	v_mfma_f32_16x16x32_bf16 v[18:21], v[160:163], v[204:207], v[18:21]
	v_mfma_f32_16x16x32_bf16 v[22:25], v[178:181], v[204:207], v[22:25]
	v_mfma_f32_16x16x32_bf16 v[6:9], v[160:163], v[212:215], v[6:9]
	v_mfma_f32_16x16x32_bf16 v[2:5], v[178:181], v[212:215], v[2:5]
	s_setprio 0
	s_barrier
	s_add_u32 s2, s2, 0x100
	s_addc_u32 s3, s3, 0
	s_add_u32 s23, s23, 0x100
	s_addc_u32 s29, s29, 0
	s_cmp_ge_i32 s36, s28
	s_mov_b32 s20, s36
	s_cbranch_scc0 .LBB0_241
